# first K iteration peeled: each accumulator's first MFMA takes SrcC=0, the 64 per-tile accumulator zeroing moves are gone
# speedup vs baseline: 1.0069x; 1.0069x over previous
; #define PG8_LAS __attribute__((address_space(3)))
; #define PG8_STAGE(bufoff, gbase, voff) do { _Pragma("unroll") for (int _i = 0; _i < 2; ++_i) \
;         __builtin_amdgcn_global_load_lds((const unsigned*)((const char*)(gbase) + (voff)[_i]), (PG8_LAS unsigned*)(lds + (bufoff) + ldsw + _i * 8192), 16, 0, 0); } while (0)
; #define PG8_LDA(dst, b, h) do { _Pragma("unroll") for (int m = 0; m < 4; ++m) _Pragma("unroll") for (int k = 0; k < 2; ++k) dst[m][k] = *(const PG8_LAS bf16x8*)(lds + PG8_SA(b, h) + aoff + m * 2048 + k * 1024); } while (0)
; #define PG8_LDB(dst, b, h) do { _Pragma("unroll") for (int n = 0; n < 2; ++n) _Pragma("unroll") for (int k = 0; k < 2; ++k) dst[n][k] = *(const PG8_LAS bf16x8*)(lds + PG8_SB(b, h) + boff + n * 2048 + k * 1024); } while (0)
; #define PG8_WAIT_V(n) asm volatile("s_waitcnt vmcnt(" #n ")" ::: "memory")
; template <class Epi, class Sched, bool ALIGN_EPI = false, bool SP2 = false, bool ABLK = false, bool BBLK = false>
; __device__ __forceinline__ void gemm_phase(PG8_LAS unsigned char* lds, const Gemm g, const Sched& S, const Epi& E) {
;     ...
;         const bool has_next = S.next(ui + 1, nxt);
;         PG8_LAS unsigned char* const rs_area = lds + STAGE_BYTES + wid * 512;
;         E.stage(cur, rs_area, wr, lane);
;         const char* nA = has_next ? (const char*)g.A + (size_t)nxt.pm * tstep : cA; const char* nB = has_next ? (const char*)g.Bt + (size_t)nxt.pn * tstep : cB;
;         for (int t = 0; t < nt; t += 2) {
;             const bool last = (t == nt - 2);
;             const char* a1 = cA + (size_t)(t + 1) * kstepA;
;             const char* a2 = last ? nA : cA + (size_t)(t + 2) * kstepA; const char* b2 = last ? nB : cB + (size_t)(t + 2) * kstepB;
;             const char* a3 = a2 + kstepA; const char* b3 = b2 + kstepB;
;             if (last && has_next) S.a_ready(nxt);
;             if constexpr (SP2) {
;             PG8_LDB(B0, 0, 0); PG8_LDB(B1, 0, 1); PG8_SCHED; PG8_LDA(At, 0, 0); PG8_STAGE(PG8_SA(1, 1), a1 + hstepA, voffA);
;             PG8_WAIT_V(8); PG8_WAIT_L(0); PG8_BAR; PG8_MMA(0, 0, At, B0); PG8_MMA(0, 1, At, B1); PG8_BAR; PG8_SCHED;
;             PG8_LDA(At, 0, 1); PG8_STAGE(PG8_SB(0, 0), b2, voffB); PG8_STAGE(PG8_SB(0, 1), b2 + hstepB, voffB); PG8_STAGE(PG8_SA(0, 0), a2, voffA);
;             PG8_WAIT_V(8); PG8_WAIT_L(0); PG8_BAR; PG8_MMA(1, 0, At, B0); PG8_MMA(1, 1, At, B1); PG8_BAR; PG8_SCHED;
.LBB0_184:
	s_lshl_b32 s10, s18, 8
	s_ashr_i32 s11, s10, 31
	s_mov_b32 m0, s64
	v_lshl_add_u64 v[4:5], s[10:11], 2, v[144:145]
	global_load_lds_dword v[4:5], off
	v_lshl_add_u64 v[4:5], v[4:5], 0, s[90:91]
	s_add_i32 m0, s64, 0x100
	s_ashr_i32 s9, s8, 31
	global_load_lds_dword v[4:5], off
	s_lshl_b64 s[10:11], s[8:9], 20
	v_readlane_b32 s16, v252, 27
	v_readlane_b32 s17, v252, 28
	s_add_u32 s10, s16, s10
	s_addc_u32 s11, s17, s11
	s_and_b64 s[16:17], s[2:3], exec
	s_cselect_b32 s9, s11, s21
	s_cselect_b32 s70, s10, s20
	s_ashr_i32 s7, s6, 31
	s_lshl_b64 s[16:17], s[6:7], 20
	s_add_u32 s16, s29, s16
	s_addc_u32 s17, s30, s17
	s_and_b64 s[24:25], s[2:3], exec
	s_cselect_b32 s7, s17, s23
	s_cselect_b32 s71, s16, s22
	s_add_u32 s20, s20, 0xc000
	s_addc_u32 s21, s21, 0
	s_add_u32 s77, s22, 0x10000
	s_addc_u32 vcc_lo, s23, 0
	s_mov_b32 vcc_hi, -2
	s_add_u32 s13, s20, 0x4000
	s_addc_u32 s22, s21, 0
	s_cmp_eq_u32 vcc_hi, 28
	s_cselect_b32 s26, s70, s13
	s_cselect_b32 s27, s9, s22
	s_cselect_b32 s24, s71, s77
	s_cselect_b32 s25, s7, vcc_lo
	s_add_u32 s22, s26, 0x8000
	s_addc_u32 s23, s27, 0
	s_add_i32 s13, 0, 0x10000
	v_add_u32_e32 v36, s13, v160
	s_add_i32 s88, 0, 0x14000
	ds_read_b128 v[152:155], v36
	ds_read_b128 v[156:159], v36 offset:1024
	ds_read_b128 v[162:165], v36 offset:2048
	ds_read_b128 v[166:169], v36 offset:3072
	v_add_u32_e32 v36, s88, v160
	ds_read_b128 v[170:173], v36
	ds_read_b128 v[174:177], v36 offset:1024
	ds_read_b128 v[178:181], v36 offset:2048
	ds_read_b128 v[182:185], v36 offset:3072
	s_add_i32 m0, s19, 0xc000
	ds_read_b128 v[186:189], v161
	ds_read_b128 v[190:193], v161 offset:1024
	ds_read_b128 v[194:197], v161 offset:2048
	ds_read_b128 v[198:201], v161 offset:3072
	ds_read_b128 v[202:205], v161 offset:4096
	ds_read_b128 v[206:209], v161 offset:5120
	ds_read_b128 v[210:213], v161 offset:6144
	ds_read_b128 v[214:217], v161 offset:7168
	global_load_lds_dwordx4 v148, s[20:21]
	s_add_i32 m0, s19, 0xe000
	s_nop 0
	global_load_lds_dwordx4 v150, s[20:21]
	s_waitcnt vmcnt(8)
	s_waitcnt lgkmcnt(0)
	v_mfma_f32_16x16x32_bf16 v[132:135], v[152:155], v[186:189], 0
	v_mfma_f32_16x16x32_bf16 v[132:135], v[156:159], v[190:193], v[132:135]
	v_mfma_f32_16x16x32_bf16 v[128:131], v[166:169], v[190:193], 0
	v_mfma_f32_16x16x32_bf16 v[128:131], v[162:165], v[186:189], v[128:131]
	s_barrier
	s_setprio 1
	v_mfma_f32_16x16x32_bf16 v[112:115], v[162:165], v[194:197], 0
	v_mfma_f32_16x16x32_bf16 v[112:115], v[166:169], v[198:201], v[112:115]
	v_mfma_f32_16x16x32_bf16 v[116:119], v[156:159], v[198:201], 0
	v_mfma_f32_16x16x32_bf16 v[116:119], v[152:155], v[194:197], v[116:119]
	v_mfma_f32_16x16x32_bf16 v[100:103], v[152:155], v[202:205], 0
	v_mfma_f32_16x16x32_bf16 v[100:103], v[156:159], v[206:209], v[100:103]
	v_mfma_f32_16x16x32_bf16 v[96:99], v[166:169], v[206:209], 0
	v_mfma_f32_16x16x32_bf16 v[96:99], v[162:165], v[202:205], v[96:99]
	v_mfma_f32_16x16x32_bf16 v[80:83], v[162:165], v[210:213], 0
	v_mfma_f32_16x16x32_bf16 v[80:83], v[166:169], v[214:217], v[80:83]
	v_mfma_f32_16x16x32_bf16 v[84:87], v[156:159], v[214:217], 0
	v_mfma_f32_16x16x32_bf16 v[84:87], v[152:155], v[210:213], v[84:87]
	v_mfma_f32_16x16x32_bf16 v[76:79], v[170:173], v[210:213], 0
	v_mfma_f32_16x16x32_bf16 v[76:79], v[174:177], v[214:217], v[76:79]
	v_mfma_f32_16x16x32_bf16 v[124:127], v[174:177], v[190:193], 0
	v_mfma_f32_16x16x32_bf16 v[124:127], v[170:173], v[186:189], v[124:127]
	v_mfma_f32_16x16x32_bf16 v[120:123], v[178:181], v[186:189], 0
	v_mfma_f32_16x16x32_bf16 v[120:123], v[182:185], v[190:193], v[120:123]
	v_mfma_f32_16x16x32_bf16 v[104:107], v[182:185], v[198:201], 0
	v_mfma_f32_16x16x32_bf16 v[104:107], v[178:181], v[194:197], v[104:107]
	v_mfma_f32_16x16x32_bf16 v[108:111], v[170:173], v[194:197], 0
	v_mfma_f32_16x16x32_bf16 v[108:111], v[174:177], v[198:201], v[108:111]
	v_mfma_f32_16x16x32_bf16 v[92:95], v[174:177], v[206:209], 0
	v_mfma_f32_16x16x32_bf16 v[92:95], v[170:173], v[202:205], v[92:95]
	v_mfma_f32_16x16x32_bf16 v[88:91], v[178:181], v[202:205], 0
	v_mfma_f32_16x16x32_bf16 v[88:91], v[182:185], v[206:209], v[88:91]
	v_mfma_f32_16x16x32_bf16 v[72:75], v[182:185], v[214:217], 0
	v_mfma_f32_16x16x32_bf16 v[72:75], v[178:181], v[210:213], v[72:75]
	s_setprio 0
	s_barrier
	s_add_i32 s13, s13, s31
	s_mov_b32 m0, s13
	ds_read_b128 v[186:189], v161 offset:16384
	ds_read_b128 v[190:193], v161 offset:17408
	ds_read_b128 v[194:197], v161 offset:18432
	ds_read_b128 v[198:201], v161 offset:19456
	ds_read_b128 v[202:205], v161 offset:20480
	ds_read_b128 v[206:209], v161 offset:21504
	ds_read_b128 v[210:213], v161 offset:22528
	ds_read_b128 v[214:217], v161 offset:23552
	global_load_lds_dwordx4 v140, s[24:25]
	s_add_i32 m0, s13, 0x2000
	s_add_u32 s68, s24, 0x4000
	s_addc_u32 s69, s25, 0
	s_add_i32 s13, s88, s31
	global_load_lds_dwordx4 v136, s[24:25]
	s_mov_b32 m0, s13
	s_nop 0
	global_load_lds_dwordx4 v140, s[68:69]
	s_add_i32 m0, s13, 0x2000
	s_nop 0
	global_load_lds_dwordx4 v136, s[68:69]
	s_mov_b32 m0, s19
	s_nop 0
	global_load_lds_dwordx4 v142, s[26:27]
	s_mov_b32 m0, s35
	s_nop 0
	global_load_lds_dwordx4 v138, s[26:27]
	s_waitcnt vmcnt(8)
	s_waitcnt lgkmcnt(0)
	v_mfma_f32_16x16x32_bf16 v[68:71], v[152:155], v[186:189], 0
	v_mfma_f32_16x16x32_bf16 v[68:71], v[156:159], v[190:193], v[68:71]
	v_mfma_f32_16x16x32_bf16 v[64:67], v[166:169], v[190:193], 0
	v_mfma_f32_16x16x32_bf16 v[64:67], v[162:165], v[186:189], v[64:67]
	s_barrier
; #define PG8_STAGE(bufoff, gbase, voff) do { _Pragma("unroll") for (int _i = 0; _i < 2; ++_i) \
;         __builtin_amdgcn_global_load_lds((const unsigned*)((const char*)(gbase) + (voff)[_i]), (PG8_LAS unsigned*)(lds + (bufoff) + ldsw + _i * 8192), 16, 0, 0); } while (0)
; #define PG8_LDA(dst, b, h) do { _Pragma("unroll") for (int m = 0; m < 4; ++m) _Pragma("unroll") for (int k = 0; k < 2; ++k) dst[m][k] = *(const PG8_LAS bf16x8*)(lds + PG8_SA(b, h) + aoff + m * 2048 + k * 1024); } while (0)
; #define PG8_LDB(dst, b, h) do { _Pragma("unroll") for (int n = 0; n < 2; ++n) _Pragma("unroll") for (int k = 0; k < 2; ++k) dst[n][k] = *(const PG8_LAS bf16x8*)(lds + PG8_SB(b, h) + boff + n * 2048 + k * 1024); } while (0)
; #define PG8_MMA(ai, bj, At, Bt) do { __builtin_amdgcn_s_setprio(1); _Pragma("unroll") for (int m = 0; m < 4; ++m) _Pragma("unroll") for (int n = 0; n < 2; ++n) _Pragma("unroll") for (int k = 0; k < 2; ++k) \
;         acc[ai][bj][m][n] = __builtin_amdgcn_mfma_f32_16x16x32_bf16(Bt[n][k], At[m][k], acc[ai][bj][m][n], 0, 0, 0); __builtin_amdgcn_s_setprio(0); } while (0)
; #define PG8_WAIT_V(n) asm volatile("s_waitcnt vmcnt(" #n ")" ::: "memory")
; #define PG8_WAIT_L(n) asm volatile("s_waitcnt lgkmcnt(" #n ")" ::: "memory")
; #define PG8_BAR __builtin_amdgcn_s_barrier()
; #define PG8_SCHED __builtin_amdgcn_sched_barrier(0)
; template <class Epi, class Sched, bool ALIGN_EPI = false, bool SP2 = false, bool ABLK = false, bool BBLK = false>
; __device__ __forceinline__ void gemm_phase(PG8_LAS unsigned char* lds, const Gemm g, const Sched& S, const Epi& E) {
;     ...
;             PG8_WAIT_V(8); PG8_WAIT_L(0); PG8_BAR; PG8_MMA(1, 0, At, B0); PG8_MMA(1, 1, At, B1); PG8_BAR; PG8_SCHED;
;             PG8_LDB(B0, 1, 0); PG8_LDB(B1, 1, 1); PG8_SCHED; PG8_LDA(At, 1, 0); PG8_STAGE(PG8_SA(0, 1), a2 + hstepA, voffA);
;             PG8_WAIT_V(8); PG8_WAIT_L(0); PG8_BAR; PG8_MMA(0, 0, At, B0); PG8_MMA(0, 1, At, B1); PG8_BAR; PG8_SCHED;
	s_setprio 1
	v_mfma_f32_16x16x32_bf16 v[48:51], v[162:165], v[194:197], 0
	v_mfma_f32_16x16x32_bf16 v[48:51], v[166:169], v[198:201], v[48:51]
	v_mfma_f32_16x16x32_bf16 v[52:55], v[156:159], v[198:201], 0
	v_mfma_f32_16x16x32_bf16 v[52:55], v[152:155], v[194:197], v[52:55]
	v_mfma_f32_16x16x32_bf16 v[32:35], v[152:155], v[202:205], 0
	v_mfma_f32_16x16x32_bf16 v[32:35], v[156:159], v[206:209], v[32:35]
	v_mfma_f32_16x16x32_bf16 v[28:31], v[166:169], v[206:209], 0
	v_mfma_f32_16x16x32_bf16 v[28:31], v[162:165], v[202:205], v[28:31]
	v_mfma_f32_16x16x32_bf16 v[12:15], v[162:165], v[210:213], 0
	v_mfma_f32_16x16x32_bf16 v[12:15], v[166:169], v[214:217], v[12:15]
	v_mfma_f32_16x16x32_bf16 v[16:19], v[156:159], v[214:217], 0
	v_mfma_f32_16x16x32_bf16 v[16:19], v[152:155], v[210:213], v[16:19]
	v_mfma_f32_16x16x32_bf16 v[8:11], v[170:173], v[210:213], 0
	v_mfma_f32_16x16x32_bf16 v[8:11], v[174:177], v[214:217], v[8:11]
	v_mfma_f32_16x16x32_bf16 v[60:63], v[174:177], v[190:193], 0
	v_mfma_f32_16x16x32_bf16 v[60:63], v[170:173], v[186:189], v[60:63]
	v_mfma_f32_16x16x32_bf16 v[56:59], v[178:181], v[186:189], 0
	v_mfma_f32_16x16x32_bf16 v[56:59], v[182:185], v[190:193], v[56:59]
	v_mfma_f32_16x16x32_bf16 v[40:43], v[182:185], v[198:201], 0
	v_mfma_f32_16x16x32_bf16 v[40:43], v[178:181], v[194:197], v[40:43]
	v_mfma_f32_16x16x32_bf16 v[44:47], v[170:173], v[194:197], 0
	v_mfma_f32_16x16x32_bf16 v[44:47], v[174:177], v[198:201], v[44:47]
	v_mfma_f32_16x16x32_bf16 v[24:27], v[174:177], v[206:209], 0
	v_mfma_f32_16x16x32_bf16 v[24:27], v[170:173], v[202:205], v[24:27]
	v_mfma_f32_16x16x32_bf16 v[20:23], v[178:181], v[202:205], 0
	v_mfma_f32_16x16x32_bf16 v[20:23], v[182:185], v[206:209], v[20:23]
	v_mfma_f32_16x16x32_bf16 v[4:7], v[182:185], v[214:217], 0
	v_mfma_f32_16x16x32_bf16 v[4:7], v[178:181], v[210:213], v[4:7]
	s_setprio 0
	s_barrier
	s_add_i32 s13, 0, 0x18000
	v_add_u32_e32 v36, s13, v160
	s_add_i32 s68, 0, 0x1c000
	ds_read_b128 v[152:155], v36
	ds_read_b128 v[156:159], v36 offset:1024
	ds_read_b128 v[162:165], v36 offset:2048
	ds_read_b128 v[166:169], v36 offset:3072
	v_add_u32_e32 v36, s68, v160
	ds_read_b128 v[170:173], v36
	ds_read_b128 v[174:177], v36 offset:1024
	ds_read_b128 v[178:181], v36 offset:2048
	ds_read_b128 v[182:185], v36 offset:3072
	s_add_u32 s26, s26, 0x4000
	s_addc_u32 s27, s27, 0
	s_mov_b32 m0, s36
	ds_read_b128 v[186:189], v161 offset:32768
	ds_read_b128 v[190:193], v161 offset:33792
	ds_read_b128 v[194:197], v161 offset:34816
	ds_read_b128 v[198:201], v161 offset:35840
	ds_read_b128 v[202:205], v161 offset:36864
	ds_read_b128 v[206:209], v161 offset:37888
	ds_read_b128 v[210:213], v161 offset:38912
	ds_read_b128 v[214:217], v161 offset:39936
	global_load_lds_dwordx4 v142, s[26:27]
	s_mov_b32 m0, s37
	s_nop 0
	global_load_lds_dwordx4 v138, s[26:27]
	s_waitcnt vmcnt(8)
	s_waitcnt lgkmcnt(0)
	v_mfma_f32_16x16x32_bf16 v[132:135], v[152:155], v[186:189], v[132:135]
	v_mfma_f32_16x16x32_bf16 v[132:135], v[156:159], v[190:193], v[132:135]
	v_mfma_f32_16x16x32_bf16 v[128:131], v[166:169], v[190:193], v[128:131]
	v_mfma_f32_16x16x32_bf16 v[128:131], v[162:165], v[186:189], v[128:131]
	s_barrier
	s_setprio 1
	v_mfma_f32_16x16x32_bf16 v[112:115], v[162:165], v[194:197], v[112:115]
	v_mfma_f32_16x16x32_bf16 v[112:115], v[166:169], v[198:201], v[112:115]
	v_mfma_f32_16x16x32_bf16 v[116:119], v[156:159], v[198:201], v[116:119]
	v_mfma_f32_16x16x32_bf16 v[116:119], v[152:155], v[194:197], v[116:119]
	v_mfma_f32_16x16x32_bf16 v[100:103], v[152:155], v[202:205], v[100:103]
	v_mfma_f32_16x16x32_bf16 v[100:103], v[156:159], v[206:209], v[100:103]
	v_mfma_f32_16x16x32_bf16 v[96:99], v[166:169], v[206:209], v[96:99]
	v_mfma_f32_16x16x32_bf16 v[96:99], v[162:165], v[202:205], v[96:99]
	v_mfma_f32_16x16x32_bf16 v[80:83], v[162:165], v[210:213], v[80:83]
	v_mfma_f32_16x16x32_bf16 v[80:83], v[166:169], v[214:217], v[80:83]
	v_mfma_f32_16x16x32_bf16 v[84:87], v[156:159], v[214:217], v[84:87]
	v_mfma_f32_16x16x32_bf16 v[84:87], v[152:155], v[210:213], v[84:87]
	v_mfma_f32_16x16x32_bf16 v[76:79], v[170:173], v[210:213], v[76:79]
	v_mfma_f32_16x16x32_bf16 v[76:79], v[174:177], v[214:217], v[76:79]
	v_mfma_f32_16x16x32_bf16 v[124:127], v[174:177], v[190:193], v[124:127]
	v_mfma_f32_16x16x32_bf16 v[124:127], v[170:173], v[186:189], v[124:127]
	v_mfma_f32_16x16x32_bf16 v[120:123], v[178:181], v[186:189], v[120:123]
	v_mfma_f32_16x16x32_bf16 v[120:123], v[182:185], v[190:193], v[120:123]
	v_mfma_f32_16x16x32_bf16 v[104:107], v[182:185], v[198:201], v[104:107]
	v_mfma_f32_16x16x32_bf16 v[104:107], v[178:181], v[194:197], v[104:107]
	v_mfma_f32_16x16x32_bf16 v[108:111], v[170:173], v[194:197], v[108:111]
	v_mfma_f32_16x16x32_bf16 v[108:111], v[174:177], v[198:201], v[108:111]
	v_mfma_f32_16x16x32_bf16 v[92:95], v[174:177], v[206:209], v[92:95]
	v_mfma_f32_16x16x32_bf16 v[92:95], v[170:173], v[202:205], v[92:95]
	v_mfma_f32_16x16x32_bf16 v[88:91], v[178:181], v[202:205], v[88:91]
	v_mfma_f32_16x16x32_bf16 v[88:91], v[182:185], v[206:209], v[88:91]
	v_mfma_f32_16x16x32_bf16 v[72:75], v[182:185], v[214:217], v[72:75]
	v_mfma_f32_16x16x32_bf16 v[72:75], v[178:181], v[210:213], v[72:75]
	s_setprio 0
	s_barrier
; #define PG8_STAGE(bufoff, gbase, voff) do { _Pragma("unroll") for (int _i = 0; _i < 2; ++_i) \
;         __builtin_amdgcn_global_load_lds((const unsigned*)((const char*)(gbase) + (voff)[_i]), (PG8_LAS unsigned*)(lds + (bufoff) + ldsw + _i * 8192), 16, 0, 0); } while (0)
; #define PG8_LDA(dst, b, h) do { _Pragma("unroll") for (int m = 0; m < 4; ++m) _Pragma("unroll") for (int k = 0; k < 2; ++k) dst[m][k] = *(const PG8_LAS bf16x8*)(lds + PG8_SA(b, h) + aoff + m * 2048 + k * 1024); } while (0)
; #define PG8_MMA(ai, bj, At, Bt) do { __builtin_amdgcn_s_setprio(1); _Pragma("unroll") for (int m = 0; m < 4; ++m) _Pragma("unroll") for (int n = 0; n < 2; ++n) _Pragma("unroll") for (int k = 0; k < 2; ++k) \
;         acc[ai][bj][m][n] = __builtin_amdgcn_mfma_f32_16x16x32_bf16(Bt[n][k], At[m][k], acc[ai][bj][m][n], 0, 0, 0); __builtin_amdgcn_s_setprio(0); } while (0)
; #define PG8_WAIT_V(n) asm volatile("s_waitcnt vmcnt(" #n ")" ::: "memory")
; #define PG8_WAIT_L(n) asm volatile("s_waitcnt lgkmcnt(" #n ")" ::: "memory")
; #define PG8_BAR __builtin_amdgcn_s_barrier()
; #define PG8_SCHED __builtin_amdgcn_sched_barrier(0)
; template <class Epi, class Sched, bool ALIGN_EPI = false, bool SP2 = false, bool ABLK = false, bool BBLK = false>
; __device__ __forceinline__ void gemm_phase(PG8_LAS unsigned char* lds, const Gemm g, const Sched& S, const Epi& E) {
;     ...
;             PG8_LDA(At, 1, 1); PG8_STAGE(PG8_SB(1, 0), b3, voffB); PG8_STAGE(PG8_SB(1, 1), b3 + hstepB, voffB); PG8_STAGE(PG8_SA(1, 0), a3, voffA);
;             PG8_WAIT_V(8); PG8_WAIT_L(0); PG8_BAR; PG8_MMA(1, 0, At, B0); PG8_MMA(1, 1, At, B1); PG8_BAR; PG8_SCHED;
	s_add_u32 s26, s24, 0x8000
	s_addc_u32 s27, s25, 0
	s_add_i32 s13, s13, s31
	s_mov_b32 m0, s13
	ds_read_b128 v[186:189], v161 offset:49152
	ds_read_b128 v[190:193], v161 offset:50176
	ds_read_b128 v[194:197], v161 offset:51200
	ds_read_b128 v[198:201], v161 offset:52224
	ds_read_b128 v[202:205], v161 offset:53248
	ds_read_b128 v[206:209], v161 offset:54272
	ds_read_b128 v[210:213], v161 offset:55296
	ds_read_b128 v[214:217], v161 offset:56320
	global_load_lds_dwordx4 v140, s[26:27]
	s_add_i32 m0, s13, 0x2000
	s_add_u32 s24, s24, 0xc000
	s_addc_u32 s25, s25, 0
	s_add_i32 s13, s68, s31
	global_load_lds_dwordx4 v136, s[26:27]
	s_mov_b32 m0, s13
	s_nop 0
	global_load_lds_dwordx4 v140, s[24:25]
	s_add_i32 m0, s13, 0x2000
	s_nop 0
	global_load_lds_dwordx4 v136, s[24:25]
	s_mov_b32 m0, s62
	s_nop 0
	global_load_lds_dwordx4 v142, s[22:23]
	s_mov_b32 m0, s63
	s_nop 0
	global_load_lds_dwordx4 v138, s[22:23]
	s_waitcnt vmcnt(8)
	s_waitcnt lgkmcnt(0)
	v_mfma_f32_16x16x32_bf16 v[68:71], v[152:155], v[186:189], v[68:71]
	v_mfma_f32_16x16x32_bf16 v[68:71], v[156:159], v[190:193], v[68:71]
	v_mfma_f32_16x16x32_bf16 v[64:67], v[166:169], v[190:193], v[64:67]
	v_mfma_f32_16x16x32_bf16 v[64:67], v[162:165], v[186:189], v[64:67]
	s_barrier
	s_setprio 1
	v_mfma_f32_16x16x32_bf16 v[48:51], v[162:165], v[194:197], v[48:51]
	v_mfma_f32_16x16x32_bf16 v[48:51], v[166:169], v[198:201], v[48:51]
	v_mfma_f32_16x16x32_bf16 v[52:55], v[156:159], v[198:201], v[52:55]
	v_mfma_f32_16x16x32_bf16 v[52:55], v[152:155], v[194:197], v[52:55]
	v_mfma_f32_16x16x32_bf16 v[32:35], v[152:155], v[202:205], v[32:35]
	v_mfma_f32_16x16x32_bf16 v[32:35], v[156:159], v[206:209], v[32:35]
	v_mfma_f32_16x16x32_bf16 v[28:31], v[166:169], v[206:209], v[28:31]
	v_mfma_f32_16x16x32_bf16 v[28:31], v[162:165], v[202:205], v[28:31]
	v_mfma_f32_16x16x32_bf16 v[12:15], v[162:165], v[210:213], v[12:15]
	v_mfma_f32_16x16x32_bf16 v[12:15], v[166:169], v[214:217], v[12:15]
	v_mfma_f32_16x16x32_bf16 v[16:19], v[156:159], v[214:217], v[16:19]
	v_mfma_f32_16x16x32_bf16 v[16:19], v[152:155], v[210:213], v[16:19]
	v_mfma_f32_16x16x32_bf16 v[8:11], v[170:173], v[210:213], v[8:11]
	v_mfma_f32_16x16x32_bf16 v[8:11], v[174:177], v[214:217], v[8:11]
	v_mfma_f32_16x16x32_bf16 v[60:63], v[174:177], v[190:193], v[60:63]
	v_mfma_f32_16x16x32_bf16 v[60:63], v[170:173], v[186:189], v[60:63]
	v_mfma_f32_16x16x32_bf16 v[56:59], v[178:181], v[186:189], v[56:59]
	v_mfma_f32_16x16x32_bf16 v[56:59], v[182:185], v[190:193], v[56:59]
	v_mfma_f32_16x16x32_bf16 v[40:43], v[182:185], v[198:201], v[40:43]
	v_mfma_f32_16x16x32_bf16 v[40:43], v[178:181], v[194:197], v[40:43]
	v_mfma_f32_16x16x32_bf16 v[44:47], v[170:173], v[194:197], v[44:47]
	v_mfma_f32_16x16x32_bf16 v[44:47], v[174:177], v[198:201], v[44:47]
	v_mfma_f32_16x16x32_bf16 v[24:27], v[174:177], v[206:209], v[24:27]
	v_mfma_f32_16x16x32_bf16 v[24:27], v[170:173], v[202:205], v[24:27]
	v_mfma_f32_16x16x32_bf16 v[20:23], v[178:181], v[202:205], v[20:23]
	v_mfma_f32_16x16x32_bf16 v[20:23], v[182:185], v[206:209], v[20:23]
	v_mfma_f32_16x16x32_bf16 v[4:7], v[182:185], v[214:217], v[4:7]
	v_mfma_f32_16x16x32_bf16 v[4:7], v[178:181], v[210:213], v[4:7]
	s_setprio 0
	s_barrier
	s_add_i32 vcc_hi, vcc_hi, 2
	s_add_u32 s20, s20, 0x10000
	s_addc_u32 s21, s21, 0
	s_add_u32 s77, s77, 0x10000
	s_addc_u32 vcc_lo, vcc_lo, 0
	s_cmp_gt_u32 vcc_hi, 29

; #define PG8_STAGE(bufoff, gbase, voff) do { _Pragma("unroll") for (int _i = 0; _i < 2; ++_i) \
;         __builtin_amdgcn_global_load_lds((const unsigned*)((const char*)(gbase) + (voff)[_i]), (PG8_LAS unsigned*)(lds + (bufoff) + ldsw + _i * 8192), 16, 0, 0); } while (0)
; #define PG8_LDA(dst, b, h) do { _Pragma("unroll") for (int m = 0; m < 4; ++m) _Pragma("unroll") for (int k = 0; k < 2; ++k) dst[m][k] = *(const PG8_LAS bf16x8*)(lds + PG8_SA(b, h) + aoff + m * 2048 + k * 1024); } while (0)
; #define PG8_LDB(dst, b, h) do { _Pragma("unroll") for (int n = 0; n < 2; ++n) _Pragma("unroll") for (int k = 0; k < 2; ++k) dst[n][k] = *(const PG8_LAS bf16x8*)(lds + PG8_SB(b, h) + boff + n * 2048 + k * 1024); } while (0)
; #define PG8_WAIT_V(n) asm volatile("s_waitcnt vmcnt(" #n ")" ::: "memory")
; #define PG8_WAIT_L(n) asm volatile("s_waitcnt lgkmcnt(" #n ")" ::: "memory")
; #define PG8_BAR __builtin_amdgcn_s_barrier()
; #define PG8_SCHED __builtin_amdgcn_sched_barrier(0)
; template <class Epi, class Sched, bool ALIGN_EPI = false, bool SP2 = false, bool ABLK = false, bool BBLK = false>
; __device__ __forceinline__ void gemm_phase(PG8_LAS unsigned char* lds, const Gemm g, const Sched& S, const Epi& E) {
;     ...
;         const char* nA = has_next ? (const char*)g.A + (size_t)nxt.pm * tstep : cA; const char* nB = has_next ? (const char*)g.Bt + (size_t)nxt.pn * tstep : cB;
;         for (int t = 0; t < nt; t += 2) {
;             const bool last = (t == nt - 2);
;             const char* a1 = cA + (size_t)(t + 1) * kstepA;
;             const char* a2 = last ? nA : cA + (size_t)(t + 2) * kstepA; const char* b2 = last ? nB : cB + (size_t)(t + 2) * kstepB;
;             const char* a3 = a2 + kstepA; const char* b3 = b2 + kstepB;
;             if (last && has_next) S.a_ready(nxt);
;             if constexpr (SP2) {
;             PG8_LDB(B0, 0, 0); PG8_LDB(B1, 0, 1); PG8_SCHED; PG8_LDA(At, 0, 0); PG8_STAGE(PG8_SA(1, 1), a1 + hstepA, voffA);
;             PG8_WAIT_V(8); PG8_WAIT_L(0); PG8_BAR; PG8_MMA(0, 0, At, B0); PG8_MMA(0, 1, At, B1); PG8_BAR; PG8_SCHED;
;             PG8_LDA(At, 0, 1); PG8_STAGE(PG8_SB(0, 0), b2, voffB); PG8_STAGE(PG8_SB(0, 1), b2 + hstepB, voffB); PG8_STAGE(PG8_SA(0, 0), a2, voffA);
;             PG8_WAIT_V(8); PG8_WAIT_L(0); PG8_BAR; PG8_MMA(1, 0, At, B0); PG8_MMA(1, 1, At, B1); PG8_BAR; PG8_SCHED;
.LBB0_438:
	s_add_u32 s10, s10, 0xc000
	s_addc_u32 s11, s11, 0
	s_add_u32 vcc_lo, s16, 0x10000
	s_addc_u32 vcc_hi, s17, 0
	s_mov_b32 s13, -2
	s_add_u32 s16, s10, 0x4000
	s_addc_u32 s17, s11, 0
	s_cmpk_eq_i32 s13, 0x54
	s_cselect_b32 s20, s0, s16
	s_cselect_b32 s21, s1, s17
	s_cselect_b32 s18, s8, vcc_lo
	s_cselect_b32 s19, s9, vcc_hi
	s_add_u32 s16, s20, 0x8000
	s_addc_u32 s17, s21, 0
	s_add_i32 s68, 0, 0x10000
	v_add_u32_e32 v36, s68, v148
	s_add_i32 s88, 0, 0x14000
	ds_read_b128 v[152:155], v36
	ds_read_b128 v[156:159], v36 offset:1024
	ds_read_b128 v[160:163], v36 offset:2048
	ds_read_b128 v[164:167], v36 offset:3072
	v_add_u32_e32 v36, s88, v148
	ds_read_b128 v[168:171], v36
	ds_read_b128 v[172:175], v36 offset:1024
	ds_read_b128 v[176:179], v36 offset:2048
	ds_read_b128 v[180:183], v36 offset:3072
	s_add_i32 m0, s27, 0xc000
	ds_read_b128 v[184:187], v150
	ds_read_b128 v[188:191], v150 offset:1024
	ds_read_b128 v[192:195], v150 offset:2048
	ds_read_b128 v[196:199], v150 offset:3072
	ds_read_b128 v[200:203], v150 offset:4096
	ds_read_b128 v[204:207], v150 offset:5120
	ds_read_b128 v[208:211], v150 offset:6144
	ds_read_b128 v[212:215], v150 offset:7168
	global_load_lds_dwordx4 v144, s[10:11]
	s_add_i32 m0, s27, 0xe000
	s_nop 0
	global_load_lds_dwordx4 v146, s[10:11]
	s_waitcnt vmcnt(8)
	s_waitcnt lgkmcnt(0)
	v_mfma_f32_16x16x32_bf16 v[132:135], v[152:155], v[184:187], 0
	v_mfma_f32_16x16x32_bf16 v[132:135], v[156:159], v[188:191], v[132:135]
	v_mfma_f32_16x16x32_bf16 v[128:131], v[164:167], v[188:191], 0
	v_mfma_f32_16x16x32_bf16 v[128:131], v[160:163], v[184:187], v[128:131]
	s_barrier
	s_setprio 1
	v_mfma_f32_16x16x32_bf16 v[120:123], v[160:163], v[192:195], 0
	v_mfma_f32_16x16x32_bf16 v[120:123], v[164:167], v[196:199], v[120:123]
	v_mfma_f32_16x16x32_bf16 v[124:127], v[156:159], v[196:199], 0
	v_mfma_f32_16x16x32_bf16 v[124:127], v[152:155], v[192:195], v[124:127]
	v_mfma_f32_16x16x32_bf16 v[108:111], v[152:155], v[200:203], 0
	v_mfma_f32_16x16x32_bf16 v[108:111], v[156:159], v[204:207], v[108:111]
	v_mfma_f32_16x16x32_bf16 v[104:107], v[164:167], v[204:207], 0
	v_mfma_f32_16x16x32_bf16 v[104:107], v[160:163], v[200:203], v[104:107]
	v_mfma_f32_16x16x32_bf16 v[88:91], v[160:163], v[208:211], 0
	v_mfma_f32_16x16x32_bf16 v[88:91], v[164:167], v[212:215], v[88:91]
	v_mfma_f32_16x16x32_bf16 v[92:95], v[156:159], v[212:215], 0
	v_mfma_f32_16x16x32_bf16 v[92:95], v[152:155], v[208:211], v[92:95]
	v_mfma_f32_16x16x32_bf16 v[76:79], v[168:171], v[208:211], 0
	v_mfma_f32_16x16x32_bf16 v[76:79], v[172:175], v[212:215], v[76:79]
	v_mfma_f32_16x16x32_bf16 v[116:119], v[172:175], v[188:191], 0
	v_mfma_f32_16x16x32_bf16 v[116:119], v[168:171], v[184:187], v[116:119]
	v_mfma_f32_16x16x32_bf16 v[112:115], v[176:179], v[184:187], 0
	v_mfma_f32_16x16x32_bf16 v[112:115], v[180:183], v[188:191], v[112:115]
	v_mfma_f32_16x16x32_bf16 v[96:99], v[180:183], v[196:199], 0
	v_mfma_f32_16x16x32_bf16 v[96:99], v[176:179], v[192:195], v[96:99]
	v_mfma_f32_16x16x32_bf16 v[100:103], v[168:171], v[192:195], 0
	v_mfma_f32_16x16x32_bf16 v[100:103], v[172:175], v[196:199], v[100:103]
	v_mfma_f32_16x16x32_bf16 v[84:87], v[172:175], v[204:207], 0
	v_mfma_f32_16x16x32_bf16 v[84:87], v[168:171], v[200:203], v[84:87]
	v_mfma_f32_16x16x32_bf16 v[80:83], v[176:179], v[200:203], 0
	v_mfma_f32_16x16x32_bf16 v[80:83], v[180:183], v[204:207], v[80:83]
	v_mfma_f32_16x16x32_bf16 v[72:75], v[180:183], v[212:215], 0
	v_mfma_f32_16x16x32_bf16 v[72:75], v[176:179], v[208:211], v[72:75]
	s_setprio 0
	s_barrier
	s_add_i32 s68, s68, s24
	s_mov_b32 m0, s68
	ds_read_b128 v[184:187], v150 offset:16384
	ds_read_b128 v[188:191], v150 offset:17408
	ds_read_b128 v[192:195], v150 offset:18432
	ds_read_b128 v[196:199], v150 offset:19456
	ds_read_b128 v[200:203], v150 offset:20480
	ds_read_b128 v[204:207], v150 offset:21504
	ds_read_b128 v[208:211], v150 offset:22528
	ds_read_b128 v[212:215], v150 offset:23552
	global_load_lds_dwordx4 v138, s[18:19]
	s_add_i32 m0, s68, 0x2000
	s_add_u32 s68, s18, 0x4000
	s_addc_u32 s69, s19, 0
	s_add_i32 s88, s88, s24
	global_load_lds_dwordx4 v142, s[18:19]
	s_mov_b32 m0, s88
	s_nop 0
	global_load_lds_dwordx4 v138, s[68:69]
	s_add_i32 m0, s88, 0x2000
	s_nop 0
	global_load_lds_dwordx4 v142, s[68:69]
	s_mov_b32 m0, s27
	s_nop 0
	global_load_lds_dwordx4 v136, s[20:21]
	s_mov_b32 m0, s28
	s_nop 0
	global_load_lds_dwordx4 v140, s[20:21]
	s_waitcnt vmcnt(8)
	s_waitcnt lgkmcnt(0)
	v_mfma_f32_16x16x32_bf16 v[68:71], v[152:155], v[184:187], 0
	v_mfma_f32_16x16x32_bf16 v[68:71], v[156:159], v[188:191], v[68:71]
	v_mfma_f32_16x16x32_bf16 v[64:67], v[164:167], v[188:191], 0
	v_mfma_f32_16x16x32_bf16 v[64:67], v[160:163], v[184:187], v[64:67]
	s_barrier
	s_setprio 1
	v_mfma_f32_16x16x32_bf16 v[56:59], v[160:163], v[192:195], 0
	v_mfma_f32_16x16x32_bf16 v[56:59], v[164:167], v[196:199], v[56:59]
	v_mfma_f32_16x16x32_bf16 v[60:63], v[156:159], v[196:199], 0
	v_mfma_f32_16x16x32_bf16 v[60:63], v[152:155], v[192:195], v[60:63]
	v_mfma_f32_16x16x32_bf16 v[44:47], v[152:155], v[200:203], 0
	v_mfma_f32_16x16x32_bf16 v[44:47], v[156:159], v[204:207], v[44:47]
	v_mfma_f32_16x16x32_bf16 v[40:43], v[164:167], v[204:207], 0
	v_mfma_f32_16x16x32_bf16 v[40:43], v[160:163], v[200:203], v[40:43]
	v_mfma_f32_16x16x32_bf16 v[20:23], v[160:163], v[208:211], 0
	v_mfma_f32_16x16x32_bf16 v[20:23], v[164:167], v[212:215], v[20:23]
	v_mfma_f32_16x16x32_bf16 v[24:27], v[156:159], v[212:215], 0
	v_mfma_f32_16x16x32_bf16 v[24:27], v[152:155], v[208:211], v[24:27]
	v_mfma_f32_16x16x32_bf16 v[8:11], v[168:171], v[208:211], 0
	v_mfma_f32_16x16x32_bf16 v[8:11], v[172:175], v[212:215], v[8:11]
	v_mfma_f32_16x16x32_bf16 v[52:55], v[172:175], v[188:191], 0
	v_mfma_f32_16x16x32_bf16 v[52:55], v[168:171], v[184:187], v[52:55]
	v_mfma_f32_16x16x32_bf16 v[48:51], v[176:179], v[184:187], 0
	v_mfma_f32_16x16x32_bf16 v[48:51], v[180:183], v[188:191], v[48:51]
	v_mfma_f32_16x16x32_bf16 v[28:31], v[180:183], v[196:199], 0
	v_mfma_f32_16x16x32_bf16 v[28:31], v[176:179], v[192:195], v[28:31]
	v_mfma_f32_16x16x32_bf16 v[32:35], v[168:171], v[192:195], 0
	v_mfma_f32_16x16x32_bf16 v[32:35], v[172:175], v[196:199], v[32:35]
	v_mfma_f32_16x16x32_bf16 v[16:19], v[172:175], v[204:207], 0
	v_mfma_f32_16x16x32_bf16 v[16:19], v[168:171], v[200:203], v[16:19]
	v_mfma_f32_16x16x32_bf16 v[12:15], v[176:179], v[200:203], 0
	v_mfma_f32_16x16x32_bf16 v[12:15], v[180:183], v[204:207], v[12:15]
	v_mfma_f32_16x16x32_bf16 v[4:7], v[180:183], v[212:215], 0
	v_mfma_f32_16x16x32_bf16 v[4:7], v[176:179], v[208:211], v[4:7]
	s_setprio 0
	s_barrier
; #define PG8_STAGE(bufoff, gbase, voff) do { _Pragma("unroll") for (int _i = 0; _i < 2; ++_i) \
;         __builtin_amdgcn_global_load_lds((const unsigned*)((const char*)(gbase) + (voff)[_i]), (PG8_LAS unsigned*)(lds + (bufoff) + ldsw + _i * 8192), 16, 0, 0); } while (0)
; #define PG8_LDA(dst, b, h) do { _Pragma("unroll") for (int m = 0; m < 4; ++m) _Pragma("unroll") for (int k = 0; k < 2; ++k) dst[m][k] = *(const PG8_LAS bf16x8*)(lds + PG8_SA(b, h) + aoff + m * 2048 + k * 1024); } while (0)
; #define PG8_WAIT_V(n) asm volatile("s_waitcnt vmcnt(" #n ")" ::: "memory")
; #define PG8_WAIT_L(n) asm volatile("s_waitcnt lgkmcnt(" #n ")" ::: "memory")
; template <class Epi, class Sched, bool ALIGN_EPI = false, bool SP2 = false, bool ABLK = false, bool BBLK = false>
; __device__ __forceinline__ void gemm_phase(PG8_LAS unsigned char* lds, const Gemm g, const Sched& S, const Epi& E) {
;     ...
;         for (int t = 0; t < nt; t += 2) {
;             const bool last = (t == nt - 2);
;             const char* a1 = cA + (size_t)(t + 1) * kstepA;
;             const char* a2 = last ? nA : cA + (size_t)(t + 2) * kstepA; const char* b2 = last ? nB : cB + (size_t)(t + 2) * kstepB;
;             const char* a3 = a2 + kstepA; const char* b3 = b2 + kstepB;
;             if (last && has_next) S.a_ready(nxt);
;             if constexpr (SP2) {
;             PG8_LDB(B0, 0, 0); PG8_LDB(B1, 0, 1); PG8_SCHED; PG8_LDA(At, 0, 0); PG8_STAGE(PG8_SA(1, 1), a1 + hstepA, voffA);
;             PG8_WAIT_V(8); PG8_WAIT_L(0); PG8_BAR; PG8_MMA(0, 0, At, B0); PG8_MMA(0, 1, At, B1); PG8_BAR; PG8_SCHED;
;             PG8_LDA(At, 0, 1); PG8_STAGE(PG8_SB(0, 0), b2, voffB); PG8_STAGE(PG8_SB(0, 1), b2 + hstepB, voffB); PG8_STAGE(PG8_SA(0, 0), a2, voffA);
;             PG8_WAIT_V(8); PG8_WAIT_L(0); PG8_BAR; PG8_MMA(1, 0, At, B0); PG8_MMA(1, 1, At, B1); PG8_BAR; PG8_SCHED;
;             PG8_LDB(B0, 1, 0); PG8_LDB(B1, 1, 1); PG8_SCHED; PG8_LDA(At, 1, 0); PG8_STAGE(PG8_SA(0, 1), a2 + hstepA, voffA);
;             PG8_WAIT_V(8); PG8_WAIT_L(0); PG8_BAR; PG8_MMA(0, 0, At, B0); PG8_MMA(0, 1, At, B1); PG8_BAR; PG8_SCHED;
;             PG8_LDA(At, 1, 1); PG8_STAGE(PG8_SB(1, 0), b3, voffB); PG8_STAGE(PG8_SB(1, 1), b3 + hstepB, voffB); PG8_STAGE(PG8_SA(1, 0), a3, voffA);
;             PG8_WAIT_V(8); PG8_WAIT_L(0); PG8_BAR; PG8_MMA(1, 0, At, B0); PG8_MMA(1, 1, At, B1); PG8_BAR; PG8_SCHED;
	s_add_i32 s68, 0, 0x18000
	v_add_u32_e32 v36, s68, v148
	s_add_i32 s69, 0, 0x1c000
	ds_read_b128 v[152:155], v36
	ds_read_b128 v[156:159], v36 offset:1024
	ds_read_b128 v[160:163], v36 offset:2048
	ds_read_b128 v[164:167], v36 offset:3072
	v_add_u32_e32 v36, s69, v148
	ds_read_b128 v[168:171], v36
	ds_read_b128 v[172:175], v36 offset:1024
	ds_read_b128 v[176:179], v36 offset:2048
	ds_read_b128 v[180:183], v36 offset:3072
	s_add_u32 s20, s20, 0x4000
	s_addc_u32 s21, s21, 0
	s_mov_b32 m0, s29
	ds_read_b128 v[184:187], v150 offset:32768
	ds_read_b128 v[188:191], v150 offset:33792
	ds_read_b128 v[192:195], v150 offset:34816
	ds_read_b128 v[196:199], v150 offset:35840
	ds_read_b128 v[200:203], v150 offset:36864
	ds_read_b128 v[204:207], v150 offset:37888
	ds_read_b128 v[208:211], v150 offset:38912
	ds_read_b128 v[212:215], v150 offset:39936
	global_load_lds_dwordx4 v136, s[20:21]
	s_mov_b32 m0, s30
	s_nop 0
	global_load_lds_dwordx4 v140, s[20:21]
	s_waitcnt vmcnt(8)
	s_waitcnt lgkmcnt(0)
	v_mfma_f32_16x16x32_bf16 v[132:135], v[152:155], v[184:187], v[132:135]
	v_mfma_f32_16x16x32_bf16 v[132:135], v[156:159], v[188:191], v[132:135]
	v_mfma_f32_16x16x32_bf16 v[128:131], v[164:167], v[188:191], v[128:131]
	v_mfma_f32_16x16x32_bf16 v[128:131], v[160:163], v[184:187], v[128:131]
	s_barrier
	s_setprio 1
	v_mfma_f32_16x16x32_bf16 v[120:123], v[160:163], v[192:195], v[120:123]
	v_mfma_f32_16x16x32_bf16 v[120:123], v[164:167], v[196:199], v[120:123]
	v_mfma_f32_16x16x32_bf16 v[124:127], v[156:159], v[196:199], v[124:127]
	v_mfma_f32_16x16x32_bf16 v[124:127], v[152:155], v[192:195], v[124:127]
	v_mfma_f32_16x16x32_bf16 v[108:111], v[152:155], v[200:203], v[108:111]
	v_mfma_f32_16x16x32_bf16 v[108:111], v[156:159], v[204:207], v[108:111]
	v_mfma_f32_16x16x32_bf16 v[104:107], v[164:167], v[204:207], v[104:107]
	v_mfma_f32_16x16x32_bf16 v[104:107], v[160:163], v[200:203], v[104:107]
	v_mfma_f32_16x16x32_bf16 v[88:91], v[160:163], v[208:211], v[88:91]
	v_mfma_f32_16x16x32_bf16 v[88:91], v[164:167], v[212:215], v[88:91]
	v_mfma_f32_16x16x32_bf16 v[92:95], v[156:159], v[212:215], v[92:95]
	v_mfma_f32_16x16x32_bf16 v[92:95], v[152:155], v[208:211], v[92:95]
	v_mfma_f32_16x16x32_bf16 v[76:79], v[168:171], v[208:211], v[76:79]
	v_mfma_f32_16x16x32_bf16 v[76:79], v[172:175], v[212:215], v[76:79]
	v_mfma_f32_16x16x32_bf16 v[116:119], v[172:175], v[188:191], v[116:119]
	v_mfma_f32_16x16x32_bf16 v[116:119], v[168:171], v[184:187], v[116:119]
	v_mfma_f32_16x16x32_bf16 v[112:115], v[176:179], v[184:187], v[112:115]
	v_mfma_f32_16x16x32_bf16 v[112:115], v[180:183], v[188:191], v[112:115]
	v_mfma_f32_16x16x32_bf16 v[96:99], v[180:183], v[196:199], v[96:99]
	v_mfma_f32_16x16x32_bf16 v[96:99], v[176:179], v[192:195], v[96:99]
	v_mfma_f32_16x16x32_bf16 v[100:103], v[168:171], v[192:195], v[100:103]
	v_mfma_f32_16x16x32_bf16 v[100:103], v[172:175], v[196:199], v[100:103]
	v_mfma_f32_16x16x32_bf16 v[84:87], v[172:175], v[204:207], v[84:87]
	v_mfma_f32_16x16x32_bf16 v[84:87], v[168:171], v[200:203], v[84:87]
	v_mfma_f32_16x16x32_bf16 v[80:83], v[176:179], v[200:203], v[80:83]
	v_mfma_f32_16x16x32_bf16 v[80:83], v[180:183], v[204:207], v[80:83]
	v_mfma_f32_16x16x32_bf16 v[72:75], v[180:183], v[212:215], v[72:75]
	v_mfma_f32_16x16x32_bf16 v[72:75], v[176:179], v[208:211], v[72:75]
	s_setprio 0
	s_barrier
	s_add_u32 s20, s18, 0x8000
	s_addc_u32 s21, s19, 0
	s_add_i32 s68, s68, s24
	s_mov_b32 m0, s68
	ds_read_b128 v[184:187], v150 offset:49152
	ds_read_b128 v[188:191], v150 offset:50176
	ds_read_b128 v[192:195], v150 offset:51200
	ds_read_b128 v[196:199], v150 offset:52224
	ds_read_b128 v[200:203], v150 offset:53248
	ds_read_b128 v[204:207], v150 offset:54272
	ds_read_b128 v[208:211], v150 offset:55296
	ds_read_b128 v[212:215], v150 offset:56320
	global_load_lds_dwordx4 v138, s[20:21]
	s_add_i32 m0, s68, 0x2000
	s_add_u32 s18, s18, 0xc000
	s_addc_u32 s19, s19, 0
	global_load_lds_dwordx4 v142, s[20:21]
	s_add_i32 s20, s69, s24
	s_mov_b32 m0, s20
	s_nop 0
	global_load_lds_dwordx4 v138, s[18:19]
	s_add_i32 m0, s20, 0x2000
	s_nop 0
	global_load_lds_dwordx4 v142, s[18:19]
	s_mov_b32 m0, s35
	s_nop 0
	global_load_lds_dwordx4 v136, s[16:17]
	s_mov_b32 m0, s70
	s_nop 0
	global_load_lds_dwordx4 v140, s[16:17]
	s_waitcnt vmcnt(8)
	s_waitcnt lgkmcnt(0)
	v_mfma_f32_16x16x32_bf16 v[68:71], v[152:155], v[184:187], v[68:71]
	v_mfma_f32_16x16x32_bf16 v[68:71], v[156:159], v[188:191], v[68:71]
	v_mfma_f32_16x16x32_bf16 v[64:67], v[164:167], v[188:191], v[64:67]
	v_mfma_f32_16x16x32_bf16 v[64:67], v[160:163], v[184:187], v[64:67]
	s_barrier
	s_setprio 1
	v_mfma_f32_16x16x32_bf16 v[56:59], v[160:163], v[192:195], v[56:59]
	v_mfma_f32_16x16x32_bf16 v[56:59], v[164:167], v[196:199], v[56:59]
	v_mfma_f32_16x16x32_bf16 v[60:63], v[156:159], v[196:199], v[60:63]
	v_mfma_f32_16x16x32_bf16 v[60:63], v[152:155], v[192:195], v[60:63]
	v_mfma_f32_16x16x32_bf16 v[44:47], v[152:155], v[200:203], v[44:47]
	v_mfma_f32_16x16x32_bf16 v[44:47], v[156:159], v[204:207], v[44:47]
	v_mfma_f32_16x16x32_bf16 v[40:43], v[164:167], v[204:207], v[40:43]
	v_mfma_f32_16x16x32_bf16 v[40:43], v[160:163], v[200:203], v[40:43]
	v_mfma_f32_16x16x32_bf16 v[20:23], v[160:163], v[208:211], v[20:23]
	v_mfma_f32_16x16x32_bf16 v[20:23], v[164:167], v[212:215], v[20:23]
	v_mfma_f32_16x16x32_bf16 v[24:27], v[156:159], v[212:215], v[24:27]
	v_mfma_f32_16x16x32_bf16 v[24:27], v[152:155], v[208:211], v[24:27]
	v_mfma_f32_16x16x32_bf16 v[8:11], v[168:171], v[208:211], v[8:11]
	v_mfma_f32_16x16x32_bf16 v[8:11], v[172:175], v[212:215], v[8:11]
	v_mfma_f32_16x16x32_bf16 v[52:55], v[172:175], v[188:191], v[52:55]
	v_mfma_f32_16x16x32_bf16 v[52:55], v[168:171], v[184:187], v[52:55]
	v_mfma_f32_16x16x32_bf16 v[48:51], v[176:179], v[184:187], v[48:51]
	v_mfma_f32_16x16x32_bf16 v[48:51], v[180:183], v[188:191], v[48:51]
	v_mfma_f32_16x16x32_bf16 v[28:31], v[180:183], v[196:199], v[28:31]
	v_mfma_f32_16x16x32_bf16 v[28:31], v[176:179], v[192:195], v[28:31]
	v_mfma_f32_16x16x32_bf16 v[32:35], v[168:171], v[192:195], v[32:35]
	v_mfma_f32_16x16x32_bf16 v[32:35], v[172:175], v[196:199], v[32:35]
	v_mfma_f32_16x16x32_bf16 v[16:19], v[172:175], v[204:207], v[16:19]
	v_mfma_f32_16x16x32_bf16 v[16:19], v[168:171], v[200:203], v[16:19]
	v_mfma_f32_16x16x32_bf16 v[12:15], v[176:179], v[200:203], v[12:15]
	v_mfma_f32_16x16x32_bf16 v[12:15], v[180:183], v[204:207], v[12:15]
	v_mfma_f32_16x16x32_bf16 v[4:7], v[180:183], v[212:215], v[4:7]
	v_mfma_f32_16x16x32_bf16 v[4:7], v[176:179], v[208:211], v[4:7]
	s_setprio 0
	s_barrier
	s_add_i32 s13, s13, 2
	s_add_u32 s10, s10, 0x10000
	s_addc_u32 s11, s11, 0
	s_add_u32 vcc_lo, vcc_lo, 0x10000
	s_addc_u32 vcc_hi, vcc_hi, 0
	s_cmpk_gt_u32 s13, 0x55

; #define PG8_LAS __attribute__((address_space(3)))
; #define PG8_STAGE(bufoff, gbase, voff) do { _Pragma("unroll") for (int _i = 0; _i < 2; ++_i) \
;         __builtin_amdgcn_global_load_lds((const unsigned*)((const char*)(gbase) + (voff)[_i]), (PG8_LAS unsigned*)(lds + (bufoff) + ldsw + _i * 8192), 16, 0, 0); } while (0)
; #define PG8_LDA(dst, b, h) do { _Pragma("unroll") for (int m = 0; m < 4; ++m) _Pragma("unroll") for (int k = 0; k < 2; ++k) dst[m][k] = *(const PG8_LAS bf16x8*)(lds + PG8_SA(b, h) + aoff + m * 2048 + k * 1024); } while (0)
; #define PG8_LDB(dst, b, h) do { _Pragma("unroll") for (int n = 0; n < 2; ++n) _Pragma("unroll") for (int k = 0; k < 2; ++k) dst[n][k] = *(const PG8_LAS bf16x8*)(lds + PG8_SB(b, h) + boff + n * 2048 + k * 1024); } while (0)
; #define PG8_WAIT_V(n) asm volatile("s_waitcnt vmcnt(" #n ")" ::: "memory")
; template <class Epi, class Sched, bool ALIGN_EPI = false, bool SP2 = false, bool ABLK = false, bool BBLK = false>
; __device__ __forceinline__ void gemm_phase(PG8_LAS unsigned char* lds, const Gemm g, const Sched& S, const Epi& E) {
;     ...
;         const bool has_next = S.next(ui + 1, nxt);
;         PG8_LAS unsigned char* const rs_area = lds + STAGE_BYTES + wid * 512;
;         E.stage(cur, rs_area, wr, lane);
;         const char* nA = has_next ? (const char*)g.A + (size_t)nxt.pm * tstep : cA; const char* nB = has_next ? (const char*)g.Bt + (size_t)nxt.pn * tstep : cB;
;         for (int t = 0; t < nt; t += 2) {
;             const bool last = (t == nt - 2);
;             const char* a1 = cA + (size_t)(t + 1) * kstepA;
;             const char* a2 = last ? nA : cA + (size_t)(t + 2) * kstepA; const char* b2 = last ? nB : cB + (size_t)(t + 2) * kstepB;
;             const char* a3 = a2 + kstepA; const char* b3 = b2 + kstepB;
;             if (last && has_next) S.a_ready(nxt);
;             if constexpr (SP2) {
;             PG8_LDB(B0, 0, 0); PG8_LDB(B1, 0, 1); PG8_SCHED; PG8_LDA(At, 0, 0); PG8_STAGE(PG8_SA(1, 1), a1 + hstepA, voffA);
;             PG8_WAIT_V(8); PG8_WAIT_L(0); PG8_BAR; PG8_MMA(0, 0, At, B0); PG8_MMA(0, 1, At, B1); PG8_BAR; PG8_SCHED;
;             PG8_LDA(At, 0, 1); PG8_STAGE(PG8_SB(0, 0), b2, voffB); PG8_STAGE(PG8_SB(0, 1), b2 + hstepB, voffB); PG8_STAGE(PG8_SA(0, 0), a2, voffA);
;             PG8_WAIT_V(8); PG8_WAIT_L(0); PG8_BAR; PG8_MMA(1, 0, At, B0); PG8_MMA(1, 1, At, B1); PG8_BAR; PG8_SCHED;
.LBB0_915:
	s_lshl_b32 s18, s0, 8
	s_ashr_i32 s19, s18, 31
	s_mov_b32 m0, s63
	v_lshl_add_u64 v[4:5], s[18:19], 2, v[144:145]
	v_lshl_add_u64 v[6:7], v[4:5], 0, s[90:91]
	global_load_lds_dword v[4:5], off
	s_add_i32 m0, s63, 0x100
	s_mov_b32 s0, s1
	global_load_lds_dword v[6:7], off
	s_ashr_i32 s1, s1, 31
	s_lshl_b64 s[10:11], s[0:1], 20
	v_readlane_b32 s16, v252, 27
	v_readlane_b32 s17, v252, 28
	s_add_u32 s10, s16, s10
	s_addc_u32 s11, s17, s11
	s_and_b64 s[16:17], s[2:3], exec
	s_cselect_b32 s1, s11, s21
	s_cselect_b32 s19, s10, s20
	s_ashr_i32 s9, s8, 31
	s_lshl_b64 s[16:17], s[8:9], 20
	v_readlane_b32 s24, v254, 5
	v_readlane_b32 s25, v254, 6
	s_add_u32 s16, s24, s16
	s_addc_u32 s17, s25, s17
	s_and_b64 s[24:25], s[2:3], exec
	s_cselect_b32 s9, s17, s23
	s_cselect_b32 s65, s16, s22
	s_add_u32 s20, s20, 0xc000
	s_addc_u32 s21, s21, 0
	s_add_u32 s70, s22, 0x10000
	s_addc_u32 s71, s23, 0
	s_mov_b32 s13, -2
	s_add_u32 s22, s20, 0x4000
	s_addc_u32 s23, s21, 0
	s_cmp_eq_u32 s13, 28
	s_cselect_b32 s26, s19, s22
	s_cselect_b32 s27, s1, s23
	s_cselect_b32 s24, s65, s70
	s_cselect_b32 s25, s9, s71
	s_add_u32 s22, s26, 0x8000
	s_addc_u32 s23, s27, 0
	s_add_i32 s68, 0, 0x10000
	v_add_u32_e32 v36, s68, v155
	s_add_i32 s77, 0, 0x14000
	ds_read_b128 v[150:153], v36
	ds_read_b128 v[158:161], v36 offset:1024
	ds_read_b128 v[162:165], v36 offset:2048
	ds_read_b128 v[166:169], v36 offset:3072
	v_add_u32_e32 v36, s77, v155
	ds_read_b128 v[170:173], v36
	ds_read_b128 v[174:177], v36 offset:1024
	ds_read_b128 v[178:181], v36 offset:2048
	ds_read_b128 v[182:185], v36 offset:3072
	s_add_i32 m0, s31, 0xc000
	ds_read_b128 v[186:189], v157
	ds_read_b128 v[190:193], v157 offset:1024
	ds_read_b128 v[194:197], v157 offset:2048
	ds_read_b128 v[198:201], v157 offset:3072
	ds_read_b128 v[202:205], v157 offset:4096
	ds_read_b128 v[206:209], v157 offset:5120
	ds_read_b128 v[210:213], v157 offset:6144
	ds_read_b128 v[214:217], v157 offset:7168
	global_load_lds_dwordx4 v146, s[20:21]
	s_add_i32 m0, s31, 0xe000
	s_nop 0
	global_load_lds_dwordx4 v148, s[20:21]
	s_waitcnt vmcnt(8)
	s_waitcnt lgkmcnt(0)
	v_mfma_f32_16x16x32_bf16 v[132:135], v[150:153], v[186:189], 0
	v_mfma_f32_16x16x32_bf16 v[132:135], v[158:161], v[190:193], v[132:135]
	v_mfma_f32_16x16x32_bf16 v[128:131], v[166:169], v[190:193], 0
	v_mfma_f32_16x16x32_bf16 v[128:131], v[162:165], v[186:189], v[128:131]
	s_barrier
	s_setprio 1
	v_mfma_f32_16x16x32_bf16 v[116:119], v[162:165], v[194:197], 0
	v_mfma_f32_16x16x32_bf16 v[116:119], v[166:169], v[198:201], v[116:119]
	v_mfma_f32_16x16x32_bf16 v[124:127], v[158:161], v[198:201], 0
	v_mfma_f32_16x16x32_bf16 v[124:127], v[150:153], v[194:197], v[124:127]
	v_mfma_f32_16x16x32_bf16 v[108:111], v[150:153], v[202:205], 0
	v_mfma_f32_16x16x32_bf16 v[108:111], v[158:161], v[206:209], v[108:111]
	v_mfma_f32_16x16x32_bf16 v[100:103], v[166:169], v[206:209], 0
	v_mfma_f32_16x16x32_bf16 v[100:103], v[162:165], v[202:205], v[100:103]
	v_mfma_f32_16x16x32_bf16 v[84:87], v[162:165], v[210:213], 0
	v_mfma_f32_16x16x32_bf16 v[84:87], v[166:169], v[214:217], v[84:87]
	v_mfma_f32_16x16x32_bf16 v[92:95], v[158:161], v[214:217], 0
	v_mfma_f32_16x16x32_bf16 v[92:95], v[150:153], v[210:213], v[92:95]
	v_mfma_f32_16x16x32_bf16 v[76:79], v[170:173], v[210:213], 0
	v_mfma_f32_16x16x32_bf16 v[76:79], v[174:177], v[214:217], v[76:79]
	v_mfma_f32_16x16x32_bf16 v[120:123], v[174:177], v[190:193], 0
	v_mfma_f32_16x16x32_bf16 v[120:123], v[170:173], v[186:189], v[120:123]
	v_mfma_f32_16x16x32_bf16 v[112:115], v[178:181], v[186:189], 0
	v_mfma_f32_16x16x32_bf16 v[112:115], v[182:185], v[190:193], v[112:115]
	v_mfma_f32_16x16x32_bf16 v[96:99], v[182:185], v[198:201], 0
	v_mfma_f32_16x16x32_bf16 v[96:99], v[178:181], v[194:197], v[96:99]
	v_mfma_f32_16x16x32_bf16 v[104:107], v[170:173], v[194:197], 0
	v_mfma_f32_16x16x32_bf16 v[104:107], v[174:177], v[198:201], v[104:107]
	v_mfma_f32_16x16x32_bf16 v[88:91], v[174:177], v[206:209], 0
	v_mfma_f32_16x16x32_bf16 v[88:91], v[170:173], v[202:205], v[88:91]
	v_mfma_f32_16x16x32_bf16 v[80:83], v[178:181], v[202:205], 0
	v_mfma_f32_16x16x32_bf16 v[80:83], v[182:185], v[206:209], v[80:83]
	v_mfma_f32_16x16x32_bf16 v[72:75], v[182:185], v[214:217], 0
	v_mfma_f32_16x16x32_bf16 v[72:75], v[178:181], v[210:213], v[72:75]
	s_setprio 0
	s_barrier
	s_add_i32 s68, s68, s29
	s_mov_b32 m0, s68
	ds_read_b128 v[186:189], v157 offset:16384
	ds_read_b128 v[190:193], v157 offset:17408
	ds_read_b128 v[194:197], v157 offset:18432
	ds_read_b128 v[198:201], v157 offset:19456
	ds_read_b128 v[202:205], v157 offset:20480
	ds_read_b128 v[206:209], v157 offset:21504
	ds_read_b128 v[210:213], v157 offset:22528
	ds_read_b128 v[214:217], v157 offset:23552
	global_load_lds_dwordx4 v140, s[24:25]
	s_add_i32 m0, s68, 0x2000
	s_add_u32 s68, s24, 0x4000
	s_addc_u32 s69, s25, 0
	s_add_i32 s77, s77, s29
	global_load_lds_dwordx4 v136, s[24:25]
	s_mov_b32 m0, s77
	s_nop 0
	global_load_lds_dwordx4 v140, s[68:69]
	s_add_i32 m0, s77, 0x2000
	s_nop 0
	global_load_lds_dwordx4 v136, s[68:69]
	s_mov_b32 m0, s31
	s_nop 0
	global_load_lds_dwordx4 v142, s[26:27]
	s_mov_b32 m0, s34
	s_nop 0
	global_load_lds_dwordx4 v138, s[26:27]
	s_waitcnt vmcnt(8)
	s_waitcnt lgkmcnt(0)
	v_mfma_f32_16x16x32_bf16 v[68:71], v[150:153], v[186:189], 0
	v_mfma_f32_16x16x32_bf16 v[68:71], v[158:161], v[190:193], v[68:71]
	v_mfma_f32_16x16x32_bf16 v[64:67], v[166:169], v[190:193], 0
	v_mfma_f32_16x16x32_bf16 v[64:67], v[162:165], v[186:189], v[64:67]
	s_barrier
; #define PG8_STAGE(bufoff, gbase, voff) do { _Pragma("unroll") for (int _i = 0; _i < 2; ++_i) \
;         __builtin_amdgcn_global_load_lds((const unsigned*)((const char*)(gbase) + (voff)[_i]), (PG8_LAS unsigned*)(lds + (bufoff) + ldsw + _i * 8192), 16, 0, 0); } while (0)
; #define PG8_LDA(dst, b, h) do { _Pragma("unroll") for (int m = 0; m < 4; ++m) _Pragma("unroll") for (int k = 0; k < 2; ++k) dst[m][k] = *(const PG8_LAS bf16x8*)(lds + PG8_SA(b, h) + aoff + m * 2048 + k * 1024); } while (0)
; #define PG8_LDB(dst, b, h) do { _Pragma("unroll") for (int n = 0; n < 2; ++n) _Pragma("unroll") for (int k = 0; k < 2; ++k) dst[n][k] = *(const PG8_LAS bf16x8*)(lds + PG8_SB(b, h) + boff + n * 2048 + k * 1024); } while (0)
; #define PG8_MMA(ai, bj, At, Bt) do { __builtin_amdgcn_s_setprio(1); _Pragma("unroll") for (int m = 0; m < 4; ++m) _Pragma("unroll") for (int n = 0; n < 2; ++n) _Pragma("unroll") for (int k = 0; k < 2; ++k) \
;         acc[ai][bj][m][n] = __builtin_amdgcn_mfma_f32_16x16x32_bf16(Bt[n][k], At[m][k], acc[ai][bj][m][n], 0, 0, 0); __builtin_amdgcn_s_setprio(0); } while (0)
; #define PG8_WAIT_V(n) asm volatile("s_waitcnt vmcnt(" #n ")" ::: "memory")
; #define PG8_WAIT_L(n) asm volatile("s_waitcnt lgkmcnt(" #n ")" ::: "memory")
; #define PG8_BAR __builtin_amdgcn_s_barrier()
; #define PG8_SCHED __builtin_amdgcn_sched_barrier(0)
; template <class Epi, class Sched, bool ALIGN_EPI = false, bool SP2 = false, bool ABLK = false, bool BBLK = false>
; __device__ __forceinline__ void gemm_phase(PG8_LAS unsigned char* lds, const Gemm g, const Sched& S, const Epi& E) {
;     ...
;             PG8_WAIT_V(8); PG8_WAIT_L(0); PG8_BAR; PG8_MMA(1, 0, At, B0); PG8_MMA(1, 1, At, B1); PG8_BAR; PG8_SCHED;
;             PG8_LDB(B0, 1, 0); PG8_LDB(B1, 1, 1); PG8_SCHED; PG8_LDA(At, 1, 0); PG8_STAGE(PG8_SA(0, 1), a2 + hstepA, voffA);
;             PG8_WAIT_V(8); PG8_WAIT_L(0); PG8_BAR; PG8_MMA(0, 0, At, B0); PG8_MMA(0, 1, At, B1); PG8_BAR; PG8_SCHED;
;             PG8_LDA(At, 1, 1); PG8_STAGE(PG8_SB(1, 0), b3, voffB); PG8_STAGE(PG8_SB(1, 1), b3 + hstepB, voffB); PG8_STAGE(PG8_SA(1, 0), a3, voffA);
	s_setprio 1
	v_mfma_f32_16x16x32_bf16 v[52:55], v[162:165], v[194:197], 0
	v_mfma_f32_16x16x32_bf16 v[52:55], v[166:169], v[198:201], v[52:55]
	v_mfma_f32_16x16x32_bf16 v[60:63], v[158:161], v[198:201], 0
	v_mfma_f32_16x16x32_bf16 v[60:63], v[150:153], v[194:197], v[60:63]
	v_mfma_f32_16x16x32_bf16 v[44:47], v[150:153], v[202:205], 0
	v_mfma_f32_16x16x32_bf16 v[44:47], v[158:161], v[206:209], v[44:47]
	v_mfma_f32_16x16x32_bf16 v[32:35], v[166:169], v[206:209], 0
	v_mfma_f32_16x16x32_bf16 v[32:35], v[162:165], v[202:205], v[32:35]
	v_mfma_f32_16x16x32_bf16 v[16:19], v[162:165], v[210:213], 0
	v_mfma_f32_16x16x32_bf16 v[16:19], v[166:169], v[214:217], v[16:19]
	v_mfma_f32_16x16x32_bf16 v[24:27], v[158:161], v[214:217], 0
	v_mfma_f32_16x16x32_bf16 v[24:27], v[150:153], v[210:213], v[24:27]
	v_mfma_f32_16x16x32_bf16 v[8:11], v[170:173], v[210:213], 0
	v_mfma_f32_16x16x32_bf16 v[8:11], v[174:177], v[214:217], v[8:11]
	v_mfma_f32_16x16x32_bf16 v[56:59], v[174:177], v[190:193], 0
	v_mfma_f32_16x16x32_bf16 v[56:59], v[170:173], v[186:189], v[56:59]
	v_mfma_f32_16x16x32_bf16 v[48:51], v[178:181], v[186:189], 0
	v_mfma_f32_16x16x32_bf16 v[48:51], v[182:185], v[190:193], v[48:51]
	v_mfma_f32_16x16x32_bf16 v[28:31], v[182:185], v[198:201], 0
	v_mfma_f32_16x16x32_bf16 v[28:31], v[178:181], v[194:197], v[28:31]
	v_mfma_f32_16x16x32_bf16 v[40:43], v[170:173], v[194:197], 0
	v_mfma_f32_16x16x32_bf16 v[40:43], v[174:177], v[198:201], v[40:43]
	v_mfma_f32_16x16x32_bf16 v[20:23], v[174:177], v[206:209], 0
	v_mfma_f32_16x16x32_bf16 v[20:23], v[170:173], v[202:205], v[20:23]
	v_mfma_f32_16x16x32_bf16 v[12:15], v[178:181], v[202:205], 0
	v_mfma_f32_16x16x32_bf16 v[12:15], v[182:185], v[206:209], v[12:15]
	v_mfma_f32_16x16x32_bf16 v[4:7], v[182:185], v[214:217], 0
	v_mfma_f32_16x16x32_bf16 v[4:7], v[178:181], v[210:213], v[4:7]
	s_setprio 0
	s_barrier
	s_add_i32 s68, 0, 0x18000
	v_add_u32_e32 v36, s68, v155
	s_add_i32 s69, 0, 0x1c000
	ds_read_b128 v[150:153], v36
	ds_read_b128 v[158:161], v36 offset:1024
	ds_read_b128 v[162:165], v36 offset:2048
	ds_read_b128 v[166:169], v36 offset:3072
	v_add_u32_e32 v36, s69, v155
	ds_read_b128 v[170:173], v36
	ds_read_b128 v[174:177], v36 offset:1024
	ds_read_b128 v[178:181], v36 offset:2048
	ds_read_b128 v[182:185], v36 offset:3072
	s_add_u32 s26, s26, 0x4000
	s_addc_u32 s27, s27, 0
	s_mov_b32 m0, s35
	ds_read_b128 v[186:189], v157 offset:32768
	ds_read_b128 v[190:193], v157 offset:33792
	ds_read_b128 v[194:197], v157 offset:34816
	ds_read_b128 v[198:201], v157 offset:35840
	ds_read_b128 v[202:205], v157 offset:36864
	ds_read_b128 v[206:209], v157 offset:37888
	ds_read_b128 v[210:213], v157 offset:38912
	ds_read_b128 v[214:217], v157 offset:39936
	global_load_lds_dwordx4 v142, s[26:27]
	s_mov_b32 m0, s36
	s_nop 0
	global_load_lds_dwordx4 v138, s[26:27]
	s_waitcnt vmcnt(8)
	s_waitcnt lgkmcnt(0)
	v_mfma_f32_16x16x32_bf16 v[132:135], v[150:153], v[186:189], v[132:135]
	v_mfma_f32_16x16x32_bf16 v[132:135], v[158:161], v[190:193], v[132:135]
	v_mfma_f32_16x16x32_bf16 v[128:131], v[166:169], v[190:193], v[128:131]
	v_mfma_f32_16x16x32_bf16 v[128:131], v[162:165], v[186:189], v[128:131]
	s_barrier
	s_setprio 1
	v_mfma_f32_16x16x32_bf16 v[116:119], v[162:165], v[194:197], v[116:119]
	v_mfma_f32_16x16x32_bf16 v[116:119], v[166:169], v[198:201], v[116:119]
	v_mfma_f32_16x16x32_bf16 v[124:127], v[158:161], v[198:201], v[124:127]
	v_mfma_f32_16x16x32_bf16 v[124:127], v[150:153], v[194:197], v[124:127]
	v_mfma_f32_16x16x32_bf16 v[108:111], v[150:153], v[202:205], v[108:111]
	v_mfma_f32_16x16x32_bf16 v[108:111], v[158:161], v[206:209], v[108:111]
	v_mfma_f32_16x16x32_bf16 v[100:103], v[166:169], v[206:209], v[100:103]
	v_mfma_f32_16x16x32_bf16 v[100:103], v[162:165], v[202:205], v[100:103]
	v_mfma_f32_16x16x32_bf16 v[84:87], v[162:165], v[210:213], v[84:87]
	v_mfma_f32_16x16x32_bf16 v[84:87], v[166:169], v[214:217], v[84:87]
	v_mfma_f32_16x16x32_bf16 v[92:95], v[158:161], v[214:217], v[92:95]
	v_mfma_f32_16x16x32_bf16 v[92:95], v[150:153], v[210:213], v[92:95]
	v_mfma_f32_16x16x32_bf16 v[76:79], v[170:173], v[210:213], v[76:79]
	v_mfma_f32_16x16x32_bf16 v[76:79], v[174:177], v[214:217], v[76:79]
	v_mfma_f32_16x16x32_bf16 v[120:123], v[174:177], v[190:193], v[120:123]
	v_mfma_f32_16x16x32_bf16 v[120:123], v[170:173], v[186:189], v[120:123]
	v_mfma_f32_16x16x32_bf16 v[112:115], v[178:181], v[186:189], v[112:115]
	v_mfma_f32_16x16x32_bf16 v[112:115], v[182:185], v[190:193], v[112:115]
	v_mfma_f32_16x16x32_bf16 v[96:99], v[182:185], v[198:201], v[96:99]
	v_mfma_f32_16x16x32_bf16 v[96:99], v[178:181], v[194:197], v[96:99]
	v_mfma_f32_16x16x32_bf16 v[104:107], v[170:173], v[194:197], v[104:107]
	v_mfma_f32_16x16x32_bf16 v[104:107], v[174:177], v[198:201], v[104:107]
	v_mfma_f32_16x16x32_bf16 v[88:91], v[174:177], v[206:209], v[88:91]
	v_mfma_f32_16x16x32_bf16 v[88:91], v[170:173], v[202:205], v[88:91]
	v_mfma_f32_16x16x32_bf16 v[80:83], v[178:181], v[202:205], v[80:83]
	v_mfma_f32_16x16x32_bf16 v[80:83], v[182:185], v[206:209], v[80:83]
	v_mfma_f32_16x16x32_bf16 v[72:75], v[182:185], v[214:217], v[72:75]
	v_mfma_f32_16x16x32_bf16 v[72:75], v[178:181], v[210:213], v[72:75]
	s_setprio 0
	s_barrier
; #define PG8_STAGE(bufoff, gbase, voff) do { _Pragma("unroll") for (int _i = 0; _i < 2; ++_i) \
;         __builtin_amdgcn_global_load_lds((const unsigned*)((const char*)(gbase) + (voff)[_i]), (PG8_LAS unsigned*)(lds + (bufoff) + ldsw + _i * 8192), 16, 0, 0); } while (0)
; #define PG8_LDA(dst, b, h) do { _Pragma("unroll") for (int m = 0; m < 4; ++m) _Pragma("unroll") for (int k = 0; k < 2; ++k) dst[m][k] = *(const PG8_LAS bf16x8*)(lds + PG8_SA(b, h) + aoff + m * 2048 + k * 1024); } while (0)
; #define PG8_MMA(ai, bj, At, Bt) do { __builtin_amdgcn_s_setprio(1); _Pragma("unroll") for (int m = 0; m < 4; ++m) _Pragma("unroll") for (int n = 0; n < 2; ++n) _Pragma("unroll") for (int k = 0; k < 2; ++k) \
;         acc[ai][bj][m][n] = __builtin_amdgcn_mfma_f32_16x16x32_bf16(Bt[n][k], At[m][k], acc[ai][bj][m][n], 0, 0, 0); __builtin_amdgcn_s_setprio(0); } while (0)
; #define PG8_WAIT_V(n) asm volatile("s_waitcnt vmcnt(" #n ")" ::: "memory")
; #define PG8_WAIT_L(n) asm volatile("s_waitcnt lgkmcnt(" #n ")" ::: "memory")
; #define PG8_BAR __builtin_amdgcn_s_barrier()
; #define PG8_SCHED __builtin_amdgcn_sched_barrier(0)
; template <class Epi, class Sched, bool ALIGN_EPI = false, bool SP2 = false, bool ABLK = false, bool BBLK = false>
; __device__ __forceinline__ void gemm_phase(PG8_LAS unsigned char* lds, const Gemm g, const Sched& S, const Epi& E) {
;     ...
;             PG8_LDA(At, 1, 1); PG8_STAGE(PG8_SB(1, 0), b3, voffB); PG8_STAGE(PG8_SB(1, 1), b3 + hstepB, voffB); PG8_STAGE(PG8_SA(1, 0), a3, voffA);
;             PG8_WAIT_V(8); PG8_WAIT_L(0); PG8_BAR; PG8_MMA(1, 0, At, B0); PG8_MMA(1, 1, At, B1); PG8_BAR; PG8_SCHED;
	s_add_u32 s26, s24, 0x8000
	s_addc_u32 s27, s25, 0
	s_add_i32 s68, s68, s29
	s_mov_b32 m0, s68
	ds_read_b128 v[186:189], v157 offset:49152
	ds_read_b128 v[190:193], v157 offset:50176
	ds_read_b128 v[194:197], v157 offset:51200
	ds_read_b128 v[198:201], v157 offset:52224
	ds_read_b128 v[202:205], v157 offset:53248
	ds_read_b128 v[206:209], v157 offset:54272
	ds_read_b128 v[210:213], v157 offset:55296
	ds_read_b128 v[214:217], v157 offset:56320
	global_load_lds_dwordx4 v140, s[26:27]
	s_add_i32 m0, s68, 0x2000
	s_add_u32 s24, s24, 0xc000
	s_addc_u32 s25, s25, 0
	global_load_lds_dwordx4 v136, s[26:27]
	s_add_i32 s26, s69, s29
	s_mov_b32 m0, s26
	s_nop 0
	global_load_lds_dwordx4 v140, s[24:25]
	s_add_i32 m0, s26, 0x2000
	s_nop 0
	global_load_lds_dwordx4 v136, s[24:25]
	s_mov_b32 m0, s37
	s_nop 0
	global_load_lds_dwordx4 v142, s[22:23]
	s_mov_b32 m0, s62
	s_nop 0
	global_load_lds_dwordx4 v138, s[22:23]
	s_waitcnt vmcnt(8)
	s_waitcnt lgkmcnt(0)
	v_mfma_f32_16x16x32_bf16 v[68:71], v[150:153], v[186:189], v[68:71]
	v_mfma_f32_16x16x32_bf16 v[68:71], v[158:161], v[190:193], v[68:71]
	v_mfma_f32_16x16x32_bf16 v[64:67], v[166:169], v[190:193], v[64:67]
	v_mfma_f32_16x16x32_bf16 v[64:67], v[162:165], v[186:189], v[64:67]
	s_barrier
	s_setprio 1
	v_mfma_f32_16x16x32_bf16 v[52:55], v[162:165], v[194:197], v[52:55]
	v_mfma_f32_16x16x32_bf16 v[52:55], v[166:169], v[198:201], v[52:55]
	v_mfma_f32_16x16x32_bf16 v[60:63], v[158:161], v[198:201], v[60:63]
	v_mfma_f32_16x16x32_bf16 v[60:63], v[150:153], v[194:197], v[60:63]
	v_mfma_f32_16x16x32_bf16 v[44:47], v[150:153], v[202:205], v[44:47]
	v_mfma_f32_16x16x32_bf16 v[44:47], v[158:161], v[206:209], v[44:47]
	v_mfma_f32_16x16x32_bf16 v[32:35], v[166:169], v[206:209], v[32:35]
	v_mfma_f32_16x16x32_bf16 v[32:35], v[162:165], v[202:205], v[32:35]
	v_mfma_f32_16x16x32_bf16 v[16:19], v[162:165], v[210:213], v[16:19]
	v_mfma_f32_16x16x32_bf16 v[16:19], v[166:169], v[214:217], v[16:19]
	v_mfma_f32_16x16x32_bf16 v[24:27], v[158:161], v[214:217], v[24:27]
	v_mfma_f32_16x16x32_bf16 v[24:27], v[150:153], v[210:213], v[24:27]
	v_mfma_f32_16x16x32_bf16 v[8:11], v[170:173], v[210:213], v[8:11]
	v_mfma_f32_16x16x32_bf16 v[8:11], v[174:177], v[214:217], v[8:11]
	v_mfma_f32_16x16x32_bf16 v[56:59], v[174:177], v[190:193], v[56:59]
	v_mfma_f32_16x16x32_bf16 v[56:59], v[170:173], v[186:189], v[56:59]
	v_mfma_f32_16x16x32_bf16 v[48:51], v[178:181], v[186:189], v[48:51]
	v_mfma_f32_16x16x32_bf16 v[48:51], v[182:185], v[190:193], v[48:51]
	v_mfma_f32_16x16x32_bf16 v[28:31], v[182:185], v[198:201], v[28:31]
	v_mfma_f32_16x16x32_bf16 v[28:31], v[178:181], v[194:197], v[28:31]
	v_mfma_f32_16x16x32_bf16 v[40:43], v[170:173], v[194:197], v[40:43]
	v_mfma_f32_16x16x32_bf16 v[40:43], v[174:177], v[198:201], v[40:43]
	v_mfma_f32_16x16x32_bf16 v[20:23], v[174:177], v[206:209], v[20:23]
	v_mfma_f32_16x16x32_bf16 v[20:23], v[170:173], v[202:205], v[20:23]
	v_mfma_f32_16x16x32_bf16 v[12:15], v[178:181], v[202:205], v[12:15]
	v_mfma_f32_16x16x32_bf16 v[12:15], v[182:185], v[206:209], v[12:15]
	v_mfma_f32_16x16x32_bf16 v[4:7], v[182:185], v[214:217], v[4:7]
	v_mfma_f32_16x16x32_bf16 v[4:7], v[178:181], v[210:213], v[4:7]
	s_setprio 0
	s_barrier
	s_add_i32 s13, s13, 2
	s_add_u32 s20, s20, 0x10000
	s_addc_u32 s21, s21, 0
	s_add_u32 s70, s70, 0x10000
	s_addc_u32 s71, s71, 0
	s_cmp_gt_u32 s13, 29

; #define PG8_LAS __attribute__((address_space(3)))
; #define PG8_STAGE(bufoff, gbase, voff) do { _Pragma("unroll") for (int _i = 0; _i < 2; ++_i) \
;         __builtin_amdgcn_global_load_lds((const unsigned*)((const char*)(gbase) + (voff)[_i]), (PG8_LAS unsigned*)(lds + (bufoff) + ldsw + _i * 8192), 16, 0, 0); } while (0)
; #define PG8_LDA(dst, b, h) do { _Pragma("unroll") for (int m = 0; m < 4; ++m) _Pragma("unroll") for (int k = 0; k < 2; ++k) dst[m][k] = *(const PG8_LAS bf16x8*)(lds + PG8_SA(b, h) + aoff + m * 2048 + k * 1024); } while (0)
; #define PG8_LDB(dst, b, h) do { _Pragma("unroll") for (int n = 0; n < 2; ++n) _Pragma("unroll") for (int k = 0; k < 2; ++k) dst[n][k] = *(const PG8_LAS bf16x8*)(lds + PG8_SB(b, h) + boff + n * 2048 + k * 1024); } while (0)
; #define PG8_WAIT_V(n) asm volatile("s_waitcnt vmcnt(" #n ")" ::: "memory")
; template <class Epi, class Sched, bool ALIGN_EPI = false, bool SP2 = false, bool ABLK = false, bool BBLK = false>
; __device__ __forceinline__ void gemm_phase(PG8_LAS unsigned char* lds, const Gemm g, const Sched& S, const Epi& E) {
;     ...
;         const bool has_next = S.next(ui + 1, nxt);
;         PG8_LAS unsigned char* const rs_area = lds + STAGE_BYTES + wid * 512;
;         E.stage(cur, rs_area, wr, lane);
;         const char* nA = has_next ? (const char*)g.A + (size_t)nxt.pm * tstep : cA; const char* nB = has_next ? (const char*)g.Bt + (size_t)nxt.pn * tstep : cB;
;         for (int t = 0; t < nt; t += 2) {
;             const bool last = (t == nt - 2);
;             const char* a1 = cA + (size_t)(t + 1) * kstepA;
;             const char* a2 = last ? nA : cA + (size_t)(t + 2) * kstepA; const char* b2 = last ? nB : cB + (size_t)(t + 2) * kstepB;
;             const char* a3 = a2 + kstepA; const char* b3 = b2 + kstepB;
;             if (last && has_next) S.a_ready(nxt);
;             if constexpr (SP2) {
;             PG8_LDB(B0, 0, 0); PG8_LDB(B1, 0, 1); PG8_SCHED; PG8_LDA(At, 0, 0); PG8_STAGE(PG8_SA(1, 1), a1 + hstepA, voffA);
;             PG8_WAIT_V(8); PG8_WAIT_L(0); PG8_BAR; PG8_MMA(0, 0, At, B0); PG8_MMA(0, 1, At, B1); PG8_BAR; PG8_SCHED;
;             PG8_LDA(At, 0, 1); PG8_STAGE(PG8_SB(0, 0), b2, voffB); PG8_STAGE(PG8_SB(0, 1), b2 + hstepB, voffB); PG8_STAGE(PG8_SA(0, 0), a2, voffA);
;             PG8_WAIT_V(8); PG8_WAIT_L(0); PG8_BAR; PG8_MMA(1, 0, At, B0); PG8_MMA(1, 1, At, B1); PG8_BAR; PG8_SCHED;
.LBB0_2110:
	s_ashr_i32 s17, s16, 31
	s_lshl_b64 s[12:13], s[16:17], 20
	s_add_u32 s18, s72, s12
	s_addc_u32 s19, s73, s13
	s_and_b64 s[12:13], s[4:5], exec
	s_cselect_b32 s12, s19, s23
	s_cselect_b32 s17, s18, s22
	s_ashr_i32 s11, s10, 31
	s_lshl_b64 s[20:21], s[10:11], 20
	v_readlane_b32 s26, v254, 3
	v_readlane_b32 s27, v254, 4
	s_add_u32 s20, s26, s20
	s_addc_u32 s21, s27, s21
	s_and_b64 s[26:27], s[4:5], exec
	s_cselect_b32 s11, s21, s25
	s_cselect_b32 s77, s20, s24
	s_add_u32 s22, s22, 0xc000
	s_addc_u32 s23, s23, 0
	s_add_u32 s82, s24, 0x10000
	s_addc_u32 vcc_lo, s25, 0
	s_mov_b32 s13, -2
	s_add_u32 s24, s22, 0x4000
	s_addc_u32 s25, s23, 0
	s_cmp_eq_u32 s13, 28
	s_cselect_b32 s28, s17, s24
	s_cselect_b32 s29, s12, s25
	s_cselect_b32 s26, s77, s82
	s_cselect_b32 s27, s11, vcc_lo
	s_add_u32 s24, s28, 0x8000
	s_addc_u32 s25, s29, 0
	s_add_i32 s68, 0, 0x10000
	v_add_u32_e32 v151, s68, v148
	s_add_i32 s88, 0, 0x14000
	ds_read_b128 v[36:39], v151
	ds_read_b128 v[152:155], v151 offset:1024
	ds_read_b128 v[156:159], v151 offset:2048
	ds_read_b128 v[160:163], v151 offset:3072
	v_add_u32_e32 v151, s88, v148
	ds_read_b128 v[164:167], v151
	ds_read_b128 v[168:171], v151 offset:1024
	ds_read_b128 v[172:175], v151 offset:2048
	ds_read_b128 v[176:179], v151 offset:3072
	s_add_i32 m0, s9, 0xc000
	ds_read_b128 v[180:183], v150
	ds_read_b128 v[184:187], v150 offset:1024
	ds_read_b128 v[188:191], v150 offset:2048
	ds_read_b128 v[192:195], v150 offset:3072
	ds_read_b128 v[196:199], v150 offset:4096
	ds_read_b128 v[200:203], v150 offset:5120
	ds_read_b128 v[204:207], v150 offset:6144
	ds_read_b128 v[208:211], v150 offset:7168
	global_load_lds_dwordx4 v144, s[22:23]
	s_add_i32 m0, s9, 0xe000
	s_nop 0
	global_load_lds_dwordx4 v146, s[22:23]
	s_waitcnt vmcnt(8)
	s_waitcnt lgkmcnt(0)
	v_mfma_f32_16x16x32_bf16 v[132:135], v[36:39], v[180:183], 0
	v_mfma_f32_16x16x32_bf16 v[132:135], v[152:155], v[184:187], v[132:135]
	v_mfma_f32_16x16x32_bf16 v[128:131], v[160:163], v[184:187], 0
	v_mfma_f32_16x16x32_bf16 v[128:131], v[156:159], v[180:183], v[128:131]
	s_barrier
	s_setprio 1
	v_mfma_f32_16x16x32_bf16 v[120:123], v[156:159], v[188:191], 0
	v_mfma_f32_16x16x32_bf16 v[120:123], v[160:163], v[192:195], v[120:123]
	v_mfma_f32_16x16x32_bf16 v[124:127], v[152:155], v[192:195], 0
	v_mfma_f32_16x16x32_bf16 v[124:127], v[36:39], v[188:191], v[124:127]
	v_mfma_f32_16x16x32_bf16 v[108:111], v[36:39], v[196:199], 0
	v_mfma_f32_16x16x32_bf16 v[108:111], v[152:155], v[200:203], v[108:111]
	v_mfma_f32_16x16x32_bf16 v[104:107], v[160:163], v[200:203], 0
	v_mfma_f32_16x16x32_bf16 v[104:107], v[156:159], v[196:199], v[104:107]
	v_mfma_f32_16x16x32_bf16 v[88:91], v[156:159], v[204:207], 0
	v_mfma_f32_16x16x32_bf16 v[88:91], v[160:163], v[208:211], v[88:91]
	v_mfma_f32_16x16x32_bf16 v[92:95], v[152:155], v[208:211], 0
	v_mfma_f32_16x16x32_bf16 v[92:95], v[36:39], v[204:207], v[92:95]
	v_mfma_f32_16x16x32_bf16 v[76:79], v[164:167], v[204:207], 0
	v_mfma_f32_16x16x32_bf16 v[76:79], v[168:171], v[208:211], v[76:79]
	v_mfma_f32_16x16x32_bf16 v[116:119], v[168:171], v[184:187], 0
	v_mfma_f32_16x16x32_bf16 v[116:119], v[164:167], v[180:183], v[116:119]
	v_mfma_f32_16x16x32_bf16 v[112:115], v[172:175], v[180:183], 0
	v_mfma_f32_16x16x32_bf16 v[112:115], v[176:179], v[184:187], v[112:115]
	v_mfma_f32_16x16x32_bf16 v[96:99], v[176:179], v[192:195], 0
	v_mfma_f32_16x16x32_bf16 v[96:99], v[172:175], v[188:191], v[96:99]
	v_mfma_f32_16x16x32_bf16 v[100:103], v[164:167], v[188:191], 0
	v_mfma_f32_16x16x32_bf16 v[100:103], v[168:171], v[192:195], v[100:103]
	v_mfma_f32_16x16x32_bf16 v[84:87], v[168:171], v[200:203], 0
	v_mfma_f32_16x16x32_bf16 v[84:87], v[164:167], v[196:199], v[84:87]
	v_mfma_f32_16x16x32_bf16 v[80:83], v[172:175], v[196:199], 0
	v_mfma_f32_16x16x32_bf16 v[80:83], v[176:179], v[200:203], v[80:83]
	v_mfma_f32_16x16x32_bf16 v[72:75], v[176:179], v[208:211], 0
	v_mfma_f32_16x16x32_bf16 v[72:75], v[172:175], v[204:207], v[72:75]
	s_setprio 0
	s_barrier
	s_add_i32 s68, s68, s34
	s_mov_b32 m0, s68
	ds_read_b128 v[180:183], v150 offset:16384
	ds_read_b128 v[184:187], v150 offset:17408
	ds_read_b128 v[188:191], v150 offset:18432
	ds_read_b128 v[192:195], v150 offset:19456
	ds_read_b128 v[196:199], v150 offset:20480
	ds_read_b128 v[200:203], v150 offset:21504
	ds_read_b128 v[204:207], v150 offset:22528
	ds_read_b128 v[208:211], v150 offset:23552
	global_load_lds_dwordx4 v138, s[26:27]
	s_add_i32 m0, s68, 0x2000
	s_add_u32 s68, s26, 0x4000
	s_addc_u32 s69, s27, 0
	s_add_i32 s88, s88, s34
	global_load_lds_dwordx4 v142, s[26:27]
	s_mov_b32 m0, s88
	s_nop 0
	global_load_lds_dwordx4 v138, s[68:69]
	s_add_i32 m0, s88, 0x2000
	s_nop 0
	global_load_lds_dwordx4 v142, s[68:69]
	s_mov_b32 m0, s9
	s_nop 0
	global_load_lds_dwordx4 v136, s[28:29]
	s_mov_b32 m0, s35
	s_nop 0
	global_load_lds_dwordx4 v140, s[28:29]
	s_waitcnt vmcnt(8)
	s_waitcnt lgkmcnt(0)
	v_mfma_f32_16x16x32_bf16 v[68:71], v[36:39], v[180:183], 0
	v_mfma_f32_16x16x32_bf16 v[68:71], v[152:155], v[184:187], v[68:71]
	v_mfma_f32_16x16x32_bf16 v[64:67], v[160:163], v[184:187], 0
	v_mfma_f32_16x16x32_bf16 v[64:67], v[156:159], v[180:183], v[64:67]
	s_barrier
; #define PG8_STAGE(bufoff, gbase, voff) do { _Pragma("unroll") for (int _i = 0; _i < 2; ++_i) \
;         __builtin_amdgcn_global_load_lds((const unsigned*)((const char*)(gbase) + (voff)[_i]), (PG8_LAS unsigned*)(lds + (bufoff) + ldsw + _i * 8192), 16, 0, 0); } while (0)
; #define PG8_LDA(dst, b, h) do { _Pragma("unroll") for (int m = 0; m < 4; ++m) _Pragma("unroll") for (int k = 0; k < 2; ++k) dst[m][k] = *(const PG8_LAS bf16x8*)(lds + PG8_SA(b, h) + aoff + m * 2048 + k * 1024); } while (0)
; #define PG8_LDB(dst, b, h) do { _Pragma("unroll") for (int n = 0; n < 2; ++n) _Pragma("unroll") for (int k = 0; k < 2; ++k) dst[n][k] = *(const PG8_LAS bf16x8*)(lds + PG8_SB(b, h) + boff + n * 2048 + k * 1024); } while (0)
; #define PG8_MMA(ai, bj, At, Bt) do { __builtin_amdgcn_s_setprio(1); _Pragma("unroll") for (int m = 0; m < 4; ++m) _Pragma("unroll") for (int n = 0; n < 2; ++n) _Pragma("unroll") for (int k = 0; k < 2; ++k) \
;         acc[ai][bj][m][n] = __builtin_amdgcn_mfma_f32_16x16x32_bf16(Bt[n][k], At[m][k], acc[ai][bj][m][n], 0, 0, 0); __builtin_amdgcn_s_setprio(0); } while (0)
; #define PG8_WAIT_V(n) asm volatile("s_waitcnt vmcnt(" #n ")" ::: "memory")
; #define PG8_WAIT_L(n) asm volatile("s_waitcnt lgkmcnt(" #n ")" ::: "memory")
; #define PG8_BAR __builtin_amdgcn_s_barrier()
; #define PG8_SCHED __builtin_amdgcn_sched_barrier(0)
; template <class Epi, class Sched, bool ALIGN_EPI = false, bool SP2 = false, bool ABLK = false, bool BBLK = false>
; __device__ __forceinline__ void gemm_phase(PG8_LAS unsigned char* lds, const Gemm g, const Sched& S, const Epi& E) {
;     ...
;             PG8_WAIT_V(8); PG8_WAIT_L(0); PG8_BAR; PG8_MMA(1, 0, At, B0); PG8_MMA(1, 1, At, B1); PG8_BAR; PG8_SCHED;
;             PG8_LDB(B0, 1, 0); PG8_LDB(B1, 1, 1); PG8_SCHED; PG8_LDA(At, 1, 0); PG8_STAGE(PG8_SA(0, 1), a2 + hstepA, voffA);
;             PG8_WAIT_V(8); PG8_WAIT_L(0); PG8_BAR; PG8_MMA(0, 0, At, B0); PG8_MMA(0, 1, At, B1); PG8_BAR; PG8_SCHED;
;             PG8_LDA(At, 1, 1); PG8_STAGE(PG8_SB(1, 0), b3, voffB); PG8_STAGE(PG8_SB(1, 1), b3 + hstepB, voffB); PG8_STAGE(PG8_SA(1, 0), a3, voffA);
	s_setprio 1
	v_mfma_f32_16x16x32_bf16 v[56:59], v[156:159], v[188:191], 0
	v_mfma_f32_16x16x32_bf16 v[56:59], v[160:163], v[192:195], v[56:59]
	v_mfma_f32_16x16x32_bf16 v[60:63], v[152:155], v[192:195], 0
	v_mfma_f32_16x16x32_bf16 v[60:63], v[36:39], v[188:191], v[60:63]
	v_mfma_f32_16x16x32_bf16 v[44:47], v[36:39], v[196:199], 0
	v_mfma_f32_16x16x32_bf16 v[44:47], v[152:155], v[200:203], v[44:47]
	v_mfma_f32_16x16x32_bf16 v[40:43], v[160:163], v[200:203], 0
	v_mfma_f32_16x16x32_bf16 v[40:43], v[156:159], v[196:199], v[40:43]
	v_mfma_f32_16x16x32_bf16 v[20:23], v[156:159], v[204:207], 0
	v_mfma_f32_16x16x32_bf16 v[20:23], v[160:163], v[208:211], v[20:23]
	v_mfma_f32_16x16x32_bf16 v[24:27], v[152:155], v[208:211], 0
	v_mfma_f32_16x16x32_bf16 v[24:27], v[36:39], v[204:207], v[24:27]
	v_mfma_f32_16x16x32_bf16 v[48:51], v[172:175], v[180:183], 0
	v_mfma_f32_16x16x32_bf16 v[32:35], v[164:167], v[188:191], 0
	v_mfma_f32_16x16x32_bf16 v[28:31], v[172:175], v[188:191], 0
	v_mfma_f32_16x16x32_bf16 v[16:19], v[164:167], v[196:199], 0
	v_mfma_f32_16x16x32_bf16 v[12:15], v[172:175], v[196:199], 0
	v_mfma_f32_16x16x32_bf16 v[8:11], v[164:167], v[204:207], 0
	v_mfma_f32_16x16x32_bf16 v[4:7], v[172:175], v[204:207], 0
	v_mfma_f32_16x16x32_bf16 v[36:39], v[164:167], v[180:183], 0
	v_mfma_f32_16x16x32_bf16 v[48:51], v[176:179], v[184:187], v[48:51]
	v_mfma_f32_16x16x32_bf16 v[32:35], v[168:171], v[192:195], v[32:35]
	v_mfma_f32_16x16x32_bf16 v[28:31], v[176:179], v[192:195], v[28:31]
	v_mfma_f32_16x16x32_bf16 v[16:19], v[168:171], v[200:203], v[16:19]
	v_mfma_f32_16x16x32_bf16 v[12:15], v[176:179], v[200:203], v[12:15]
	v_mfma_f32_16x16x32_bf16 v[8:11], v[168:171], v[208:211], v[8:11]
	v_mfma_f32_16x16x32_bf16 v[4:7], v[176:179], v[208:211], v[4:7]
	v_mfma_f32_16x16x32_bf16 v[36:39], v[168:171], v[184:187], v[36:39]
	s_setprio 0
	s_barrier
	s_add_i32 s68, 0, 0x18000
	v_add_u32_e32 v151, s68, v148
	s_add_i32 s69, 0, 0x1c000
	ds_read_b128 v[52:55], v151
	ds_read_b128 v[152:155], v151 offset:1024
	ds_read_b128 v[156:159], v151 offset:2048
	ds_read_b128 v[160:163], v151 offset:3072
	v_add_u32_e32 v151, s69, v148
	ds_read_b128 v[164:167], v151
	ds_read_b128 v[168:171], v151 offset:1024
	ds_read_b128 v[172:175], v151 offset:2048
	ds_read_b128 v[176:179], v151 offset:3072
	s_add_u32 s28, s28, 0x4000
	s_addc_u32 s29, s29, 0
	s_mov_b32 m0, s36
	ds_read_b128 v[180:183], v150 offset:32768
	ds_read_b128 v[184:187], v150 offset:33792
	ds_read_b128 v[188:191], v150 offset:34816
	ds_read_b128 v[192:195], v150 offset:35840
	ds_read_b128 v[196:199], v150 offset:36864
	ds_read_b128 v[200:203], v150 offset:37888
	ds_read_b128 v[204:207], v150 offset:38912
	ds_read_b128 v[208:211], v150 offset:39936
	global_load_lds_dwordx4 v136, s[28:29]
	s_mov_b32 m0, s37
	s_nop 0
	global_load_lds_dwordx4 v140, s[28:29]
	s_waitcnt vmcnt(8)
	s_waitcnt lgkmcnt(0)
	v_mfma_f32_16x16x32_bf16 v[132:135], v[52:55], v[180:183], v[132:135]
	v_mfma_f32_16x16x32_bf16 v[132:135], v[152:155], v[184:187], v[132:135]
	v_mfma_f32_16x16x32_bf16 v[128:131], v[160:163], v[184:187], v[128:131]
	v_mfma_f32_16x16x32_bf16 v[128:131], v[156:159], v[180:183], v[128:131]
	s_barrier
	s_setprio 1
	v_mfma_f32_16x16x32_bf16 v[120:123], v[156:159], v[188:191], v[120:123]
	v_mfma_f32_16x16x32_bf16 v[120:123], v[160:163], v[192:195], v[120:123]
	v_mfma_f32_16x16x32_bf16 v[124:127], v[152:155], v[192:195], v[124:127]
	v_mfma_f32_16x16x32_bf16 v[124:127], v[52:55], v[188:191], v[124:127]
	v_mfma_f32_16x16x32_bf16 v[108:111], v[52:55], v[196:199], v[108:111]
	v_mfma_f32_16x16x32_bf16 v[108:111], v[152:155], v[200:203], v[108:111]
	v_mfma_f32_16x16x32_bf16 v[104:107], v[160:163], v[200:203], v[104:107]
	v_mfma_f32_16x16x32_bf16 v[104:107], v[156:159], v[196:199], v[104:107]
	v_mfma_f32_16x16x32_bf16 v[88:91], v[156:159], v[204:207], v[88:91]
	v_mfma_f32_16x16x32_bf16 v[88:91], v[160:163], v[208:211], v[88:91]
	v_mfma_f32_16x16x32_bf16 v[92:95], v[152:155], v[208:211], v[92:95]
	v_mfma_f32_16x16x32_bf16 v[92:95], v[52:55], v[204:207], v[92:95]
	v_mfma_f32_16x16x32_bf16 v[76:79], v[164:167], v[204:207], v[76:79]
	v_mfma_f32_16x16x32_bf16 v[76:79], v[168:171], v[208:211], v[76:79]
	v_mfma_f32_16x16x32_bf16 v[116:119], v[168:171], v[184:187], v[116:119]
	v_mfma_f32_16x16x32_bf16 v[116:119], v[164:167], v[180:183], v[116:119]
	v_mfma_f32_16x16x32_bf16 v[112:115], v[172:175], v[180:183], v[112:115]
	v_mfma_f32_16x16x32_bf16 v[112:115], v[176:179], v[184:187], v[112:115]
	v_mfma_f32_16x16x32_bf16 v[96:99], v[176:179], v[192:195], v[96:99]
	v_mfma_f32_16x16x32_bf16 v[96:99], v[172:175], v[188:191], v[96:99]
	v_mfma_f32_16x16x32_bf16 v[100:103], v[164:167], v[188:191], v[100:103]
	v_mfma_f32_16x16x32_bf16 v[100:103], v[168:171], v[192:195], v[100:103]
	v_mfma_f32_16x16x32_bf16 v[84:87], v[168:171], v[200:203], v[84:87]
	v_mfma_f32_16x16x32_bf16 v[84:87], v[164:167], v[196:199], v[84:87]
	v_mfma_f32_16x16x32_bf16 v[80:83], v[172:175], v[196:199], v[80:83]
	v_mfma_f32_16x16x32_bf16 v[80:83], v[176:179], v[200:203], v[80:83]
	v_mfma_f32_16x16x32_bf16 v[72:75], v[176:179], v[208:211], v[72:75]
	v_mfma_f32_16x16x32_bf16 v[72:75], v[172:175], v[204:207], v[72:75]
	s_setprio 0
	s_barrier
; #define PG8_STAGE(bufoff, gbase, voff) do { _Pragma("unroll") for (int _i = 0; _i < 2; ++_i) \
;         __builtin_amdgcn_global_load_lds((const unsigned*)((const char*)(gbase) + (voff)[_i]), (PG8_LAS unsigned*)(lds + (bufoff) + ldsw + _i * 8192), 16, 0, 0); } while (0)
; #define PG8_LDA(dst, b, h) do { _Pragma("unroll") for (int m = 0; m < 4; ++m) _Pragma("unroll") for (int k = 0; k < 2; ++k) dst[m][k] = *(const PG8_LAS bf16x8*)(lds + PG8_SA(b, h) + aoff + m * 2048 + k * 1024); } while (0)
; #define PG8_MMA(ai, bj, At, Bt) do { __builtin_amdgcn_s_setprio(1); _Pragma("unroll") for (int m = 0; m < 4; ++m) _Pragma("unroll") for (int n = 0; n < 2; ++n) _Pragma("unroll") for (int k = 0; k < 2; ++k) \
;         acc[ai][bj][m][n] = __builtin_amdgcn_mfma_f32_16x16x32_bf16(Bt[n][k], At[m][k], acc[ai][bj][m][n], 0, 0, 0); __builtin_amdgcn_s_setprio(0); } while (0)
; #define PG8_WAIT_V(n) asm volatile("s_waitcnt vmcnt(" #n ")" ::: "memory")
; #define PG8_WAIT_L(n) asm volatile("s_waitcnt lgkmcnt(" #n ")" ::: "memory")
; #define PG8_BAR __builtin_amdgcn_s_barrier()
; #define PG8_SCHED __builtin_amdgcn_sched_barrier(0)
; template <class Epi, class Sched, bool ALIGN_EPI = false, bool SP2 = false, bool ABLK = false, bool BBLK = false>
; __device__ __forceinline__ void gemm_phase(PG8_LAS unsigned char* lds, const Gemm g, const Sched& S, const Epi& E) {
;     ...
;             PG8_LDA(At, 1, 1); PG8_STAGE(PG8_SB(1, 0), b3, voffB); PG8_STAGE(PG8_SB(1, 1), b3 + hstepB, voffB); PG8_STAGE(PG8_SA(1, 0), a3, voffA);
;             PG8_WAIT_V(8); PG8_WAIT_L(0); PG8_BAR; PG8_MMA(1, 0, At, B0); PG8_MMA(1, 1, At, B1); PG8_BAR; PG8_SCHED;
	s_add_u32 s28, s26, 0x8000
	s_addc_u32 s29, s27, 0
	s_add_i32 s68, s68, s34
	s_mov_b32 m0, s68
	ds_read_b128 v[180:183], v150 offset:49152
	ds_read_b128 v[184:187], v150 offset:50176
	ds_read_b128 v[188:191], v150 offset:51200
	ds_read_b128 v[192:195], v150 offset:52224
	ds_read_b128 v[196:199], v150 offset:53248
	ds_read_b128 v[200:203], v150 offset:54272
	ds_read_b128 v[204:207], v150 offset:55296
	ds_read_b128 v[208:211], v150 offset:56320
	global_load_lds_dwordx4 v138, s[28:29]
	s_add_i32 m0, s68, 0x2000
	s_add_u32 s26, s26, 0xc000
	s_addc_u32 s27, s27, 0
	global_load_lds_dwordx4 v142, s[28:29]
	s_add_i32 s28, s69, s34
	s_mov_b32 m0, s28
	s_nop 0
	global_load_lds_dwordx4 v138, s[26:27]
	s_add_i32 m0, s28, 0x2000
	s_nop 0
	global_load_lds_dwordx4 v142, s[26:27]
	s_mov_b32 m0, s64
	s_nop 0
	global_load_lds_dwordx4 v136, s[24:25]
	s_mov_b32 m0, s65
	s_nop 0
	global_load_lds_dwordx4 v140, s[24:25]
	s_waitcnt vmcnt(8)
	s_waitcnt lgkmcnt(0)
	v_mfma_f32_16x16x32_bf16 v[68:71], v[52:55], v[180:183], v[68:71]
	v_mfma_f32_16x16x32_bf16 v[68:71], v[152:155], v[184:187], v[68:71]
	v_mfma_f32_16x16x32_bf16 v[64:67], v[160:163], v[184:187], v[64:67]
	v_mfma_f32_16x16x32_bf16 v[64:67], v[156:159], v[180:183], v[64:67]
	s_barrier
	s_setprio 1
	v_mfma_f32_16x16x32_bf16 v[56:59], v[156:159], v[188:191], v[56:59]
	v_mfma_f32_16x16x32_bf16 v[56:59], v[160:163], v[192:195], v[56:59]
	v_mfma_f32_16x16x32_bf16 v[60:63], v[152:155], v[192:195], v[60:63]
	v_mfma_f32_16x16x32_bf16 v[60:63], v[52:55], v[188:191], v[60:63]
	v_mfma_f32_16x16x32_bf16 v[44:47], v[52:55], v[196:199], v[44:47]
	v_mfma_f32_16x16x32_bf16 v[44:47], v[152:155], v[200:203], v[44:47]
	v_mfma_f32_16x16x32_bf16 v[40:43], v[160:163], v[200:203], v[40:43]
	v_mfma_f32_16x16x32_bf16 v[40:43], v[156:159], v[196:199], v[40:43]
	v_mfma_f32_16x16x32_bf16 v[20:23], v[156:159], v[204:207], v[20:23]
	v_mfma_f32_16x16x32_bf16 v[20:23], v[160:163], v[208:211], v[20:23]
	v_mfma_f32_16x16x32_bf16 v[24:27], v[152:155], v[208:211], v[24:27]
	v_mfma_f32_16x16x32_bf16 v[24:27], v[52:55], v[204:207], v[24:27]
	v_mfma_f32_16x16x32_bf16 v[36:39], v[164:167], v[180:183], v[36:39]
	v_mfma_f32_16x16x32_bf16 v[52:55], v[168:171], v[184:187], v[36:39]
	v_mfma_f32_16x16x32_bf16 v[36:39], v[172:175], v[180:183], v[48:51]
	v_mfma_f32_16x16x32_bf16 v[32:35], v[164:167], v[188:191], v[32:35]
	v_mfma_f32_16x16x32_bf16 v[28:31], v[172:175], v[188:191], v[28:31]
	v_mfma_f32_16x16x32_bf16 v[16:19], v[164:167], v[196:199], v[16:19]
	v_mfma_f32_16x16x32_bf16 v[12:15], v[172:175], v[196:199], v[12:15]
	v_mfma_f32_16x16x32_bf16 v[8:11], v[164:167], v[204:207], v[8:11]
	v_mfma_f32_16x16x32_bf16 v[4:7], v[172:175], v[204:207], v[4:7]
	v_mfma_f32_16x16x32_bf16 v[48:51], v[176:179], v[184:187], v[36:39]
	v_mfma_f32_16x16x32_bf16 v[32:35], v[168:171], v[192:195], v[32:35]
	v_mfma_f32_16x16x32_bf16 v[28:31], v[176:179], v[192:195], v[28:31]
	v_mfma_f32_16x16x32_bf16 v[16:19], v[168:171], v[200:203], v[16:19]
	v_mfma_f32_16x16x32_bf16 v[12:15], v[176:179], v[200:203], v[12:15]
	v_mfma_f32_16x16x32_bf16 v[8:11], v[168:171], v[208:211], v[8:11]
	v_mfma_f32_16x16x32_bf16 v[4:7], v[176:179], v[208:211], v[4:7]
	s_setprio 0
	s_barrier
	s_add_i32 s13, s13, 2
	s_add_u32 s22, s22, 0x10000
	s_addc_u32 s23, s23, 0
	s_add_u32 s82, s82, 0x10000
	s_addc_u32 vcc_lo, vcc_lo, 0
	s_cmp_gt_u32 s13, 29
